# fox fast path (no-rescale) + L2 prefetch dummies + scan deserialize
# baseline (speedup 1.0000x reference)
; DI void fox_unit(const Params& p, int hf, int bl, int fh, int qb, unsigned char* shm, int tid, bool dry = false) {
;     ...
;   f32x4 o[2][4];
; #pragma unroll
;   for (int mi = 0; mi < 2; ++mi)
; #pragma unroll
;     for (int d = 0; d < 4; ++d) o[mi][d] = (f32x4){0.f, 0.f, 0.f, 0.f};
;   float mrun[2] = {-1e30f, -1e30f}, lsum[2] = {0.f, 0.f};
.LBB0_481:
	v_mov_b32_e32 v129, 0
	s_andn2_b64 vcc, exec, s[4:5]
	v_mov_b32_e32 v128, v129
	v_mov_b32_e32 v143, v129
	v_mov_b32_e32 v142, v129
	v_mov_b32_e32 v145, v129
	v_mov_b32_e32 v144, v129
	v_mov_b32_e32 v139, v129
	v_mov_b32_e32 v138, v129
	v_mov_b32_e32 v141, v129
	v_mov_b32_e32 v140, v129
	v_mov_b32_e32 v135, v129
	v_mov_b32_e32 v134, v129
	v_mov_b32_e32 v137, v129
	v_mov_b32_e32 v136, v129
	v_mov_b32_e32 v131, v129
	v_mov_b32_e32 v130, v129
	v_mov_b32_e32 v133, v129
	v_mov_b32_e32 v132, v129
	v_mov_b32_e32 v123, v129
	v_mov_b32_e32 v122, v129
	v_mov_b32_e32 v125, v129
	v_mov_b32_e32 v124, v129
	v_mov_b32_e32 v119, v129
	v_mov_b32_e32 v118, v129
	v_mov_b32_e32 v121, v129
	v_mov_b32_e32 v120, v129
	v_mov_b32_e32 v115, v129
	v_mov_b32_e32 v114, v129
	v_mov_b32_e32 v117, v129
	v_mov_b32_e32 v116, v129
	v_mov_b32_e32 v111, v129
	v_mov_b32_e32 v110, v129
	v_mov_b32_e32 v113, v129
	v_mov_b32_e32 v112, v129
	s_cbranch_vccnz .LBB0_635
	v_or_b32_e32 v212, 31, v28
	v_lshlrev_b32_e32 v28, 2, v27
	v_lshlrev_b32_e32 v26, 6, v27
	v_and_b32_e32 v29, 32, v28
	v_bitop3_b32 v213, v26, v29, v24 bitop3:0x36
	v_lshrrev_b32_e32 v24, 2, v27
	v_or_b32_e32 v24, v209, v24
	v_mov_b32_e32 v112, 0
	v_and_b32_e32 v214, 12, v28
	v_mul_u32_u24_e32 v215, 0x90, v24
	v_add_u32_e32 v216, 64, v205
	v_add_u32_e32 v217, 64, v25
	v_mov_b32_e32 v219, 0xf149f2ca
	v_mov_b32_e32 v113, v112
	v_mov_b32_e32 v110, v112
	v_mov_b32_e32 v111, v112
	v_mov_b32_e32 v116, v112
	v_mov_b32_e32 v117, v112
	v_mov_b32_e32 v114, v112
	v_mov_b32_e32 v115, v112
	v_mov_b32_e32 v120, v112
	v_mov_b32_e32 v121, v112
	v_mov_b32_e32 v118, v112
	v_mov_b32_e32 v119, v112
	v_mov_b32_e32 v124, v112
	v_mov_b32_e32 v125, v112
	v_mov_b32_e32 v122, v112
	v_mov_b32_e32 v123, v112
	v_mov_b32_e32 v132, v112
	v_mov_b32_e32 v133, v112
	v_mov_b32_e32 v130, v112
	v_mov_b32_e32 v131, v112
	v_mov_b32_e32 v136, v112
	v_mov_b32_e32 v137, v112
	v_mov_b32_e32 v134, v112
	v_mov_b32_e32 v135, v112
	v_mov_b32_e32 v140, v112
	v_mov_b32_e32 v141, v112
	v_mov_b32_e32 v138, v112
	v_mov_b32_e32 v139, v112
	v_mov_b32_e32 v144, v112
	v_mov_b32_e32 v145, v112
	v_mov_b32_e32 v142, v112
	v_mov_b32_e32 v143, v112
	v_mov_b32_e32 v128, v112
	v_mov_b32_e32 v129, v112
	v_mov_b32_e32 v218, 0xf149f2ca
	v_mov_b32_e32 v224, 0x7149f2ca
	v_mov_b32_e32 v225, v224
	v_mov_b32_e32 v226, v224
	v_mov_b32_e32 v227, v224
	v_mov_b32_e32 v228, v224
	v_mov_b32_e32 v229, v224
	v_mov_b32_e32 v230, v224
	v_mov_b32_e32 v231, v224

; DI f32x4 mmaT(bf16x8 a_m, bf16x8 b_n, f32x4 c) { return __builtin_amdgcn_mfma_f32_16x16x32_bf16(b_n, a_m, c, 0, 0, 0); }
; DI v4i16_t tr_rd(const bf16_t* a) { return __builtin_amdgcn_ds_read_tr16_b64_v4i16((LDSP v4i16_t*)a); }
; DI float shx(float v, int m, int lane) { return __int_as_float(__builtin_amdgcn_ds_bpermute((lane ^ m) << 2, __float_as_int(v))); }
; template <bool DIAG>
; DI void fox_tile(const bf16_t* sK, const bf16_t* sV, const float* sFk, const bf16x8 (&qf)[2][2], f32x4 (&o)[2][4], float (&mrun)[2], float (&lsum)[2], int key0, int qg0, int fr, int fq, int lane) {
;     ...
;   const int kof = (fr * 64 + fq * 16) ^ ((fr >> 3) << 5);
; #pragma unroll
;   for (int t = 0; t < 4; ++t) {
;     const bf16x8 k0 = *(const bf16x8*)((const unsigned char*)sK + (t * 2) * 1024 + kof), k1 = *(const bf16x8*)((const unsigned char*)sK + (t * 2 + 1) * 1024 + kof);
; #pragma unroll
;     for (int mi = 0; mi < 2; ++mi) { s[mi][t] = mmaT(qf[mi][0], k0, (f32x4){0.f, 0.f, 0.f, 0.f}); s[mi][t] = mmaT(qf[mi][1], k1, s[mi][t]); }
;   }
;   f32x4 fk[4];
; #pragma unroll
;   for (int t = 0; t < 4; ++t) fk[t] = *(const f32x4*)(sFk + 16 * t + 4 * fq);
;   __builtin_amdgcn_sched_barrier(0);
;   bf16x8 vf[2][4];
; #pragma unroll
;   for (int k2 = 0; k2 < 2; ++k2)
; #pragma unroll
;     for (int d = 0; d < 4; ++d) {
;       const bf16_t* a = sV + (32 * k2 + 4 * fq + (fr >> 2)) * 72 + 16 * d + 4 * (fr & 3);
;       const v4i16_t lo = tr_rd(a), hi = tr_rd(a + 16 * 72);
;       vf[k2][d] = __builtin_shufflevector(lo, hi, 0, 1, 2, 3, 4, 5, 6, 7);
;     }
;   __builtin_amdgcn_sched_barrier(0);
; #pragma unroll
;   for (int mi = 0; mi < 2; ++mi) {
;     float mx = -INFINITY;
; #pragma unroll
;     for (int t = 0; t < 4; ++t)
; #pragma unroll
;       for (int j = 0; j < 4; ++j) {
;         float x = __builtin_fmaf(s[mi][t][j], SC2, fk[t][j]);
;         if (DIAG) { if (key0 + 16 * t + 4 * fq + j > qg0 + 16 * mi) x = -INFINITY; }
;         s[mi][t][j] = x; mx = fmaxf(mx, x);
;       }
;     mx = fmaxf(mx, shx(mx, 16, lane)); mx = fmaxf(mx, shx(mx, 32, lane));
.LBB0_489:
	s_mul_i32 s4, s21, 0x4900
	s_add_i32 s4, s4, 32
	v_add_u32_e32 v24, s4, v213
	ds_read_b128 v[64:67], v24
	ds_read_b128 v[68:71], v24 offset:1024
	ds_read_b128 v[56:59], v24 offset:2048
	ds_read_b128 v[60:63], v24 offset:3072
	ds_read_b128 v[48:51], v24 offset:4096
	ds_read_b128 v[52:55], v24 offset:5120
	ds_read_b128 v[40:43], v24 offset:6144
	ds_read_b128 v[44:47], v24 offset:7168
	v_lshl_add_u32 v24, v209, 2, s4
	ds_read_b128 v[36:39], v24 offset:18432
	ds_read_b128 v[32:35], v24 offset:18496
	ds_read_b128 v[28:31], v24 offset:18560
	ds_read_b128 v[24:27], v24 offset:18624
	v_lshl_add_u32 v72, v214, 1, s4
	s_cmp_lt_i32 s22, s17
	s_mov_b64 s[4:5], -1
	v_add_u32_e32 v221, v72, v215
	s_cbranch_scc1 .LBB0_491
	s_waitcnt lgkmcnt(11)
	v_mfma_f32_16x16x32_bf16 v[72:75], v[64:67], v[0:3], 0
	s_waitcnt lgkmcnt(10)
	v_mfma_f32_16x16x32_bf16 v[146:149], v[68:71], v[4:7], v[72:75]
	v_mfma_f32_16x16x32_bf16 v[72:75], v[64:67], v[8:11], 0
	v_mfma_f32_16x16x32_bf16 v[164:167], v[68:71], v[12:15], v[72:75]
	s_waitcnt lgkmcnt(9)
	v_mfma_f32_16x16x32_bf16 v[72:75], v[56:59], v[0:3], 0
	s_waitcnt lgkmcnt(8)
	v_mfma_f32_16x16x32_bf16 v[150:153], v[60:63], v[4:7], v[72:75]
	v_mfma_f32_16x16x32_bf16 v[72:75], v[56:59], v[8:11], 0
	v_mfma_f32_16x16x32_bf16 v[222:225], v[60:63], v[12:15], v[72:75]
	s_waitcnt lgkmcnt(7)
	v_mfma_f32_16x16x32_bf16 v[72:75], v[48:51], v[0:3], 0
	s_waitcnt lgkmcnt(6)
	v_mfma_f32_16x16x32_bf16 v[154:157], v[52:55], v[4:7], v[72:75]
	v_mfma_f32_16x16x32_bf16 v[72:75], v[48:51], v[8:11], 0
	v_mfma_f32_16x16x32_bf16 v[226:229], v[52:55], v[12:15], v[72:75]
	s_waitcnt lgkmcnt(5)
	v_mfma_f32_16x16x32_bf16 v[72:75], v[40:43], v[0:3], 0
	s_waitcnt lgkmcnt(4)
	v_mfma_f32_16x16x32_bf16 v[172:175], v[44:47], v[4:7], v[72:75]
	v_mfma_f32_16x16x32_bf16 v[72:75], v[40:43], v[8:11], 0
	v_mfma_f32_16x16x32_bf16 v[104:107], v[44:47], v[12:15], v[72:75]
	ds_read_b64_tr_b16 v[100:101], v221 offset:9216
	ds_read_b64_tr_b16 v[92:93], v221 offset:9248
	ds_read_b64_tr_b16 v[96:97], v221 offset:9280
	ds_read_b64_tr_b16 v[88:89], v221 offset:9312
	ds_read_b64_tr_b16 v[102:103], v221 offset:11520
	ds_read_b64_tr_b16 v[94:95], v221 offset:11552
	ds_read_b64_tr_b16 v[98:99], v221 offset:11584
	ds_read_b64_tr_b16 v[90:91], v221 offset:11616
	ds_read_b64_tr_b16 v[84:85], v221 offset:13824
	ds_read_b64_tr_b16 v[80:81], v221 offset:13856
	ds_read_b64_tr_b16 v[76:77], v221 offset:13888
	ds_read_b64_tr_b16 v[72:73], v221 offset:13920
	ds_read_b64_tr_b16 v[86:87], v221 offset:16128
	ds_read_b64_tr_b16 v[82:83], v221 offset:16160
	ds_read_b64_tr_b16 v[78:79], v221 offset:16192
	ds_read_b64_tr_b16 v[74:75], v221 offset:16224
	v_add_u32_e32 v159, s18, v209
	s_waitcnt lgkmcnt(14)
	v_fmamk_f32 v147, v147, 0x3e38aa3b, v37
	v_cmp_lt_i32_e64 s[4:5], v159, v206
	v_add_u32_e32 v177, 2, v159
	v_fmamk_f32 v148, v148, 0x3e38aa3b, v38
	v_cndmask_b32_e64 v147, v200, v147, s[4:5]
	v_cmp_le_i32_e64 s[4:5], v177, v206
	v_add_u32_e32 v179, 3, v159
	v_fmamk_f32 v149, v149, 0x3e38aa3b, v39
	v_cndmask_b32_e64 v148, v200, v148, s[4:5]
	v_cmp_le_i32_e64 s[4:5], v179, v206
	v_add_u32_e32 v176, 16, v159
	v_fmamk_f32 v146, v146, 0x3e38aa3b, v36
	v_cmp_gt_i32_e32 vcc, v159, v206
	v_cndmask_b32_e64 v149, v200, v149, s[4:5]
	v_fmamk_f32 v150, v150, 0x3e38aa3b, v32
	v_cmp_le_i32_e64 s[4:5], v176, v206
	v_cndmask_b32_e32 v146, v146, v200, vcc
	s_mov_b32 s22, 0xff800000
	v_cndmask_b32_e64 v176, v200, v150, s[4:5]
	v_fmamk_f32 v150, v151, 0x3e38aa3b, v33
	v_add_u32_e32 v151, 17, v159
	v_max3_f32 v158, v146, s22, v147
	v_cmp_le_i32_e64 s[4:5], v151, v206
	v_add_u32_e32 v181, 18, v159
	v_max3_f32 v158, v158, v148, v149
	v_cndmask_b32_e64 v178, v200, v150, s[4:5]
	v_fmamk_f32 v152, v152, 0x3e38aa3b, v34
	v_cmp_le_i32_e64 s[4:5], v181, v206
	v_max3_f32 v150, v158, v176, v178
	v_add_u32_e32 v183, 32, v159
	v_cndmask_b32_e64 v158, v200, v152, s[4:5]
	v_fmamk_f32 v152, v153, 0x3e38aa3b, v35
	v_add_u32_e32 v153, 19, v159
	v_cmp_le_i32_e64 s[4:5], v153, v206
	v_add_u32_e32 v185, 34, v159
	v_add_u32_e32 v189, 48, v159
	v_cndmask_b32_e64 v180, v200, v152, s[4:5]
	v_fmamk_f32 v152, v154, 0x3e38aa3b, v28
	v_cmp_le_i32_e64 s[4:5], v183, v206
	v_add_u32_e32 v191, 50, v159
	v_max3_f32 v150, v150, v158, v180
	v_cndmask_b32_e64 v182, v200, v152, s[4:5]
	v_fmamk_f32 v152, v155, 0x3e38aa3b, v29
	v_add_u32_e32 v155, 33, v159
	v_cmp_le_i32_e64 s[4:5], v155, v206
	v_fmamk_f32 v104, v104, 0x3e38aa3b, v24
	s_nop 0
	v_cndmask_b32_e64 v184, v200, v152, s[4:5]
	v_fmamk_f32 v152, v156, 0x3e38aa3b, v30
	v_cmp_le_i32_e64 s[4:5], v185, v206
	v_max3_f32 v150, v150, v182, v184
	s_nop 0
	v_cndmask_b32_e64 v186, v200, v152, s[4:5]
	v_fmamk_f32 v152, v157, 0x3e38aa3b, v31
	v_add_u32_e32 v157, 35, v159
	v_cmp_le_i32_e64 s[4:5], v157, v206
	s_nop 1
	v_cndmask_b32_e64 v187, v200, v152, s[4:5]
	v_fmamk_f32 v152, v172, 0x3e38aa3b, v24
	v_cmp_le_i32_e64 s[4:5], v189, v206
	v_max3_f32 v150, v150, v186, v187
	s_nop 0
	v_cndmask_b32_e64 v188, v200, v152, s[4:5]
	v_fmamk_f32 v152, v173, 0x3e38aa3b, v25
	v_add_u32_e32 v173, 49, v159
	v_cmp_le_i32_e64 s[4:5], v173, v206
	s_nop 1
	v_cndmask_b32_e64 v190, v200, v152, s[4:5]
	v_fmamk_f32 v152, v174, 0x3e38aa3b, v26
	v_cmp_le_i32_e64 s[4:5], v191, v206
	v_max3_f32 v150, v150, v188, v190
	s_nop 0
	v_cndmask_b32_e64 v194, v200, v152, s[4:5]
	v_fmamk_f32 v152, v175, 0x3e38aa3b, v27
	v_add_u32_e32 v175, 51, v159
	v_cmp_le_i32_e64 s[4:5], v175, v206
	s_nop 1
	v_cndmask_b32_e64 v202, v200, v152, s[4:5]
	v_max3_f32 v150, v150, v194, v202
	ds_bpermute_b32 v152, v204, v150
	v_cmp_le_i32_e64 s[4:5], v159, v207
	s_waitcnt lgkmcnt(0)
	v_max_f32_e32 v152, v152, v152
	v_max_f32_e32 v150, v150, v152
	ds_bpermute_b32 v152, v169, v150
	s_waitcnt lgkmcnt(0)
; DI unsigned pk2(float lo, float hi) { unsigned r; asm volatile("v_cvt_pk_bf16_f32 %0, %1, %2" : "=v"(r) : "v"(lo), "v"(hi)); return r; }
; DI float ex2(float x) { return __builtin_amdgcn_exp2f(x); }
; DI f32x4 mmaT(bf16x8 a_m, bf16x8 b_n, f32x4 c) { return __builtin_amdgcn_mfma_f32_16x16x32_bf16(b_n, a_m, c, 0, 0, 0); }
; DI float shx(float v, int m, int lane) { return __int_as_float(__builtin_amdgcn_ds_bpermute((lane ^ m) << 2, __float_as_int(v))); }
; template <bool DIAG>
; DI void fox_tile(const bf16_t* sK, const bf16_t* sV, const float* sFk, const bf16x8 (&qf)[2][2], f32x4 (&o)[2][4], float (&mrun)[2], float (&lsum)[2], int key0, int qg0, int fr, int fq, int lane) {
;     ...
;     mx = fmaxf(mx, shx(mx, 16, lane)); mx = fmaxf(mx, shx(mx, 32, lane));
;     const float mnew = fmaxf(mrun[mi], mx), alpha = ex2(mrun[mi] - mnew);
;     mrun[mi] = mnew;
;     float ps = 0.f;
; #pragma unroll
;     for (int t = 0; t < 4; ++t)
; #pragma unroll
;       for (int j = 0; j < 4; ++j) { const float pv = ex2(s[mi][t][j] - mnew); s[mi][t][j] = pv; ps += pv; }
;     lsum[mi] = lsum[mi] * alpha + ps;
; #pragma unroll
;     for (int d = 0; d < 4; ++d) o[mi][d] *= alpha;
;   }
; #pragma unroll
;   for (int k2 = 0; k2 < 2; ++k2) {
;     bf16x8 pa[2];
; #pragma unroll
;     for (int mi = 0; mi < 2; ++mi) pa[mi] = mk8(pk2(s[mi][2 * k2][0], s[mi][2 * k2][1]), pk2(s[mi][2 * k2][2], s[mi][2 * k2][3]), pk2(s[mi][2 * k2 + 1][0], s[mi][2 * k2 + 1][1]), pk2(s[mi][2 * k2 + 1][2], s[mi][2 * k2 + 1][3]));
; #pragma unroll
;     for (int d = 0; d < 4; ++d) {
; #pragma unroll
;       for (int mi = 0; mi < 2; ++mi) o[mi][d] = mmaT(pa[mi], vf[k2][d], o[mi][d]);
	v_max3_f32 v220, v219, v150, v152
	v_sub_f32_e32 v147, v147, v220
	v_exp_f32_e32 v150, v147
	v_sub_f32_e32 v147, v148, v220
	v_exp_f32_e32 v148, v147
	v_sub_f32_e32 v147, v149, v220
	v_exp_f32_e32 v152, v147
	v_sub_f32_e32 v147, v176, v220
	v_exp_f32_e32 v156, v147
	v_sub_f32_e32 v147, v178, v220
	v_exp_f32_e32 v154, v147
	v_sub_f32_e32 v147, v158, v220
	v_exp_f32_e32 v158, v147
	v_sub_f32_e32 v147, v180, v220
	v_exp_f32_e32 v174, v147
	v_sub_f32_e32 v147, v182, v220
	v_exp_f32_e32 v172, v147
	v_sub_f32_e32 v147, v184, v220
	v_exp_f32_e32 v176, v147
	v_sub_f32_e32 v147, v186, v220
	v_exp_f32_e32 v180, v147
	v_sub_f32_e32 v147, v187, v220
	v_exp_f32_e32 v178, v147
	v_sub_f32_e32 v147, v188, v220
	v_exp_f32_e32 v182, v147
	v_sub_f32_e32 v147, v190, v220
	v_exp_f32_e32 v186, v147
	v_sub_f32_e32 v147, v194, v220
	v_exp_f32_e32 v184, v147
	v_sub_f32_e32 v147, v202, v220
	v_exp_f32_e32 v190, v147
	v_fmamk_f32 v147, v164, 0x3e38aa3b, v36
	v_cndmask_b32_e64 v147, v200, v147, s[4:5]
	v_fmamk_f32 v149, v165, 0x3e38aa3b, v37
	v_cmp_lt_i32_e64 s[4:5], v159, v207
	v_fmamk_f32 v164, v166, 0x3e38aa3b, v38
	v_sub_f32_e32 v230, v219, v220
	v_cndmask_b32_e64 v149, v200, v149, s[4:5]
	v_cmp_le_i32_e64 s[4:5], v177, v207
	v_max3_f32 v159, v147, s22, v149
	v_exp_f32_e32 v188, v230
	v_cndmask_b32_e64 v177, v200, v164, s[4:5]
	v_fmamk_f32 v164, v167, 0x3e38aa3b, v39
	v_cmp_le_i32_e64 s[4:5], v179, v207
	v_pk_mul_f32 v[166:167], v[140:141], v[188:189] op_sel_hi:[1,0]
	v_pk_mul_f32 v[230:231], v[132:133], v[188:189] op_sel_hi:[1,0]
	v_cndmask_b32_e64 v179, v200, v164, s[4:5]
	v_fmamk_f32 v164, v222, 0x3e38aa3b, v32
	v_cndmask_b32_e32 v187, v164, v200, vcc
	v_fmamk_f32 v164, v223, 0x3e38aa3b, v33
	v_cmp_le_i32_e32 vcc, v151, v207
	v_max3_f32 v159, v159, v177, v179
	v_sub_f32_e32 v146, v146, v220
	v_cndmask_b32_e32 v194, v200, v164, vcc
	v_max3_f32 v151, v159, v187, v194
	v_fmamk_f32 v159, v224, 0x3e38aa3b, v34
	v_cmp_le_i32_e32 vcc, v181, v207
	v_fmamk_f32 v164, v225, 0x3e38aa3b, v35
	v_pk_mul_f32 v[224:225], v[134:135], v[188:189] op_sel_hi:[1,0]
	v_cndmask_b32_e32 v159, v200, v159, vcc
	v_cmp_le_i32_e32 vcc, v153, v207
	v_fmamk_f32 v153, v226, 0x3e38aa3b, v28
	v_exp_f32_e32 v146, v146
	v_cndmask_b32_e32 v181, v200, v164, vcc
	v_cmp_le_i32_e32 vcc, v183, v207
	v_max3_f32 v151, v151, v159, v181
	v_pk_mul_f32 v[164:165], v[138:139], v[188:189] op_sel_hi:[1,0]
	v_cndmask_b32_e32 v183, v200, v153, vcc
	v_fmamk_f32 v153, v227, 0x3e38aa3b, v29
	v_cmp_le_i32_e32 vcc, v155, v207
	v_pk_mul_f32 v[226:227], v[136:137], v[188:189] op_sel_hi:[1,0]
	v_cvt_pk_bf16_f32 v236, v146, v150
	v_cvt_pk_bf16_f32 v237, v148, v152
	v_cvt_pk_bf16_f32 v238, v156, v154
	v_cvt_pk_bf16_f32 v239, v158, v174
	s_nop 0
	v_cndmask_b32_e32 v202, v200, v153, vcc
	v_fmamk_f32 v153, v228, 0x3e38aa3b, v30
	v_cmp_le_i32_e32 vcc, v185, v207
	v_max3_f32 v151, v151, v183, v202
	v_mfma_f32_16x16x32_bf16 v[164:167], v[92:95], v[236:239], v[164:167]
	v_cndmask_b32_e32 v185, v200, v153, vcc
	v_fmamk_f32 v153, v229, 0x3e38aa3b, v31
	v_cmp_le_i32_e32 vcc, v157, v207
	v_pk_mul_f32 v[228:229], v[130:131], v[188:189] op_sel_hi:[1,0]
	v_mfma_f32_16x16x32_bf16 v[224:227], v[96:99], v[236:239], v[224:227]
	v_cndmask_b32_e32 v223, v200, v153, vcc
	v_cmp_le_i32_e32 vcc, v189, v207
	v_max3_f32 v151, v151, v185, v223
	v_mfma_f32_16x16x32_bf16 v[228:231], v[88:91], v[236:239], v[228:231]
	v_cndmask_b32_e32 v244, v200, v104, vcc
	v_fmamk_f32 v104, v105, 0x3e38aa3b, v25
	v_cmp_le_i32_e32 vcc, v173, v207
	v_fmamk_f32 v105, v106, 0x3e38aa3b, v26
	s_mov_b64 s[4:5], 0
	v_cndmask_b32_e32 v245, v200, v104, vcc
	v_cmp_le_i32_e32 vcc, v191, v207
	v_max3_f32 v104, v151, v244, v245
	s_nop 0
	v_cndmask_b32_e32 v191, v200, v105, vcc
	v_fmamk_f32 v105, v107, 0x3e38aa3b, v27
	v_cmp_le_i32_e32 vcc, v175, v207
	v_pk_mul_f32 v[106:107], v[144:145], v[188:189] op_sel_hi:[1,0]
	s_nop 0
	v_cndmask_b32_e32 v249, v200, v105, vcc
	v_max3_f32 v151, v104, v191, v249
	ds_bpermute_b32 v153, v204, v151
	v_pk_mul_f32 v[104:105], v[142:143], v[188:189] op_sel_hi:[1,0]
	s_waitcnt lgkmcnt(0)
	v_max_f32_e32 v153, v153, v153
	v_max_f32_e32 v151, v151, v153
	ds_bpermute_b32 v153, v169, v151
	v_mfma_f32_16x16x32_bf16 v[104:107], v[100:103], v[236:239], v[104:107]
	s_waitcnt lgkmcnt(0)
; template <bool DIAG>
; DI void fox_tile(const bf16_t* sK, const bf16_t* sV, const float* sFk, const bf16x8 (&qf)[2][2], f32x4 (&o)[2][4], float (&mrun)[2], float (&lsum)[2], int key0, int qg0, int fr, int fq, int lane) {
;     ...
;   const int kof = (fr * 64 + fq * 16) ^ ((fr >> 3) << 5);
; #pragma unroll
;   for (int t = 0; t < 4; ++t) {
;     const bf16x8 k0 = *(const bf16x8*)((const unsigned char*)sK + (t * 2) * 1024 + kof), k1 = *(const bf16x8*)((const unsigned char*)sK + (t * 2 + 1) * 1024 + kof);
; #pragma unroll
;     for (int mi = 0; mi < 2; ++mi) { s[mi][t] = mmaT(qf[mi][0], k0, (f32x4){0.f, 0.f, 0.f, 0.f}); s[mi][t] = mmaT(qf[mi][1], k1, s[mi][t]); }
;   }
;   f32x4 fk[4];
; #pragma unroll
;   for (int t = 0; t < 4; ++t) fk[t] = *(const f32x4*)(sFk + 16 * t + 4 * fq);
;   __builtin_amdgcn_sched_barrier(0);
;   bf16x8 vf[2][4];
; #pragma unroll
;   for (int k2 = 0; k2 < 2; ++k2)
; #pragma unroll
;     for (int d = 0; d < 4; ++d) {
;       const bf16_t* a = sV + (32 * k2 + 4 * fq + (fr >> 2)) * 72 + 16 * d + 4 * (fr & 3);
;       const v4i16_t lo = tr_rd(a), hi = tr_rd(a + 16 * 72);
;       vf[k2][d] = __builtin_shufflevector(lo, hi, 0, 1, 2, 3, 4, 5, 6, 7);
;     }
;   __builtin_amdgcn_sched_barrier(0);
; #pragma unroll
;   for (int mi = 0; mi < 2; ++mi) {
;     float mx = -INFINITY;
; #pragma unroll
;     for (int t = 0; t < 4; ++t)
; #pragma unroll
;       for (int j = 0; j < 4; ++j) {
;         float x = __builtin_fmaf(s[mi][t][j], SC2, fk[t][j]);
;     ...
;     const float mnew = fmaxf(mrun[mi], mx), alpha = ex2(mrun[mi] - mnew);
;     mrun[mi] = mnew;
;     float ps = 0.f;
; #pragma unroll
;     for (int t = 0; t < 4; ++t)
; #pragma unroll
;       for (int j = 0; j < 4; ++j) { const float pv = ex2(s[mi][t][j] - mnew); s[mi][t][j] = pv; ps += pv; }
;     lsum[mi] = lsum[mi] * alpha + ps;
; #pragma unroll
;     for (int d = 0; d < 4; ++d) o[mi][d] *= alpha;
;   }
; #pragma unroll
;   for (int k2 = 0; k2 < 2; ++k2) {
;     bf16x8 pa[2];
; #pragma unroll
;     for (int mi = 0; mi < 2; ++mi) pa[mi] = mk8(pk2(s[mi][2 * k2][0], s[mi][2 * k2][1]), pk2(s[mi][2 * k2][2], s[mi][2 * k2][3]), pk2(s[mi][2 * k2 + 1][0], s[mi][2 * k2 + 1][1]), pk2(s[mi][2 * k2 + 1][2], s[mi][2 * k2 + 1][3]));
; #pragma unroll
;     for (int d = 0; d < 4; ++d) {
; #pragma unroll
;       for (int mi = 0; mi < 2; ++mi) o[mi][d] = mmaT(pa[mi], vf[k2][d], o[mi][d]);
;     }
	v_max3_f32 v222, v218, v151, v153
	v_sub_f32_e32 v173, v218, v222
	v_exp_f32_e32 v189, v173
	v_sub_f32_e32 v149, v149, v222
	v_sub_f32_e32 v155, v187, v222
	v_sub_f32_e32 v147, v147, v222
	v_mov_b32_e32 v248, v189
	v_exp_f32_e32 v151, v149
	v_sub_f32_e32 v149, v177, v222
	v_sub_f32_e32 v153, v179, v222
	v_exp_f32_e32 v157, v155
	v_sub_f32_e32 v155, v194, v222
	v_sub_f32_e32 v159, v159, v222
	v_sub_f32_e32 v175, v181, v222
	v_pk_mul_f32 v[234:235], v[124:125], v[248:249] op_sel_hi:[1,0]
	v_pk_mul_f32 v[232:233], v[122:123], v[248:249] op_sel_hi:[1,0]
	v_exp_f32_e32 v147, v147
	v_exp_f32_e32 v149, v149
	v_exp_f32_e32 v153, v153
	v_exp_f32_e32 v155, v155
	v_exp_f32_e32 v159, v159
	v_exp_f32_e32 v175, v175
	v_cvt_pk_bf16_f32 v240, v147, v151
	v_cvt_pk_bf16_f32 v241, v149, v153
	v_cvt_pk_bf16_f32 v242, v157, v155
	v_cvt_pk_bf16_f32 v243, v159, v175
	v_sub_f32_e32 v177, v183, v222
	v_mfma_f32_16x16x32_bf16 v[100:103], v[100:103], v[240:243], v[232:235]
	v_sub_f32_e32 v179, v185, v222
	v_exp_f32_e32 v173, v177
	v_sub_f32_e32 v177, v202, v222
	v_pk_mul_f32 v[234:235], v[120:121], v[248:249] op_sel_hi:[1,0]
	v_pk_mul_f32 v[232:233], v[118:119], v[248:249] op_sel_hi:[1,0]
	v_exp_f32_e32 v181, v179
	v_sub_f32_e32 v179, v223, v222
	v_mfma_f32_16x16x32_bf16 v[232:235], v[92:95], v[240:243], v[232:235]
	v_sub_f32_e32 v92, v244, v222
	v_exp_f32_e32 v183, v92
	v_sub_f32_e32 v92, v245, v222
	v_exp_f32_e32 v187, v92
	v_pk_mul_f32 v[94:95], v[116:117], v[248:249] op_sel_hi:[1,0]
	v_pk_mul_f32 v[92:93], v[114:115], v[248:249] op_sel_hi:[1,0]
	v_exp_f32_e32 v177, v177
	v_exp_f32_e32 v179, v179
	v_mfma_f32_16x16x32_bf16 v[244:247], v[96:99], v[240:243], v[92:95]
	s_nop 2
	v_sub_f32_e32 v92, v191, v222
	v_exp_f32_e32 v185, v92
	v_sub_f32_e32 v92, v249, v222
	v_exp_f32_e32 v191, v92
	v_pk_mul_f32 v[94:95], v[112:113], v[248:249] op_sel_hi:[1,0]
	v_pk_mul_f32 v[92:93], v[110:111], v[248:249] op_sel_hi:[1,0]
	s_nop 1
	v_mfma_f32_16x16x32_bf16 v[236:239], v[88:91], v[240:243], v[92:95]
	v_cvt_pk_bf16_f32 v240, v172, v176
	v_cvt_pk_bf16_f32 v241, v180, v178
	v_cvt_pk_bf16_f32 v242, v182, v186
	v_cvt_pk_bf16_f32 v243, v184, v190
	v_cvt_pk_bf16_f32 v248, v173, v177
	v_cvt_pk_bf16_f32 v249, v181, v179
	v_cvt_pk_bf16_f32 v250, v183, v187
	v_cvt_pk_bf16_f32 v251, v185, v191
	s_nop 0
	v_mfma_f32_16x16x32_bf16 v[88:91], v[84:87], v[240:243], v[104:107]
	v_mfma_f32_16x16x32_bf16 v[92:95], v[84:87], v[248:251], v[100:103]
	v_add_f32_e64 v84, v146, 0
	v_add_f32_e64 v85, v147, 0
	v_pk_add_f32 v[96:97], v[150:151], v[84:85]
	v_mfma_f32_16x16x32_bf16 v[84:87], v[80:83], v[240:243], v[164:167]
	v_add_f32_e64 v96, v148, v96
	v_add_f32_e64 v97, v149, v97
	v_pk_add_f32 v[96:97], v[152:153], v[96:97]
	s_nop 0
	v_pk_add_f32 v[100:101], v[156:157], v[96:97]
	v_mfma_f32_16x16x32_bf16 v[96:99], v[80:83], v[248:251], v[232:235]
	v_add_f32_e64 v80, v154, v100
	v_add_f32_e64 v81, v155, v101
	v_pk_add_f32 v[80:81], v[158:159], v[80:81]
	s_nop 0
	v_pk_add_f32 v[100:101], v[174:175], v[80:81]
	v_mfma_f32_16x16x32_bf16 v[80:83], v[76:79], v[240:243], v[224:227]
	v_add_f32_e64 v100, v172, v100
	v_add_f32_e64 v101, v173, v101
	v_pk_add_f32 v[100:101], v[176:177], v[100:101]
	s_nop 0
	v_pk_add_f32 v[104:105], v[180:181], v[100:101]
	v_mfma_f32_16x16x32_bf16 v[100:103], v[76:79], v[248:251], v[244:247]
	v_add_f32_e64 v76, v178, v104
	v_add_f32_e64 v77, v179, v105
	v_pk_add_f32 v[76:77], v[182:183], v[76:77]
	s_nop 0
	v_pk_add_f32 v[104:105], v[186:187], v[76:77]
	v_mfma_f32_16x16x32_bf16 v[76:79], v[72:75], v[240:243], v[228:231]
	v_add_f32_e64 v104, v184, v104
	v_add_f32_e64 v105, v185, v105
	v_pk_add_f32 v[104:105], v[190:191], v[104:105]
	v_mfma_f32_16x16x32_bf16 v[72:75], v[72:75], v[248:251], v[236:239]
	v_fma_f32 v104, v128, v188, v104
	v_fma_f32 v105, v129, v189, v105
.LBB0_491:
	s_andn2_b64 vcc, exec, s[4:5]
	s_cbranch_vccnz .LBB0_493
	s_waitcnt lgkmcnt(11)
	v_mfma_f32_16x16x32_bf16 v[72:75], v[64:67], v[0:3], v[224:227]
	v_mfma_f32_16x16x32_bf16 v[84:87], v[64:67], v[8:11], v[228:231]
	s_waitcnt lgkmcnt(10)
	v_mfma_f32_16x16x32_bf16 v[72:75], v[68:71], v[4:7], v[72:75]
	v_mfma_f32_16x16x32_bf16 v[84:87], v[68:71], v[12:15], v[84:87]
	s_waitcnt lgkmcnt(9)
	v_mfma_f32_16x16x32_bf16 v[76:79], v[56:59], v[0:3], v[224:227]
	v_mfma_f32_16x16x32_bf16 v[88:91], v[56:59], v[8:11], v[228:231]
	s_waitcnt lgkmcnt(8)
	v_mfma_f32_16x16x32_bf16 v[76:79], v[60:63], v[4:7], v[76:79]
	v_mfma_f32_16x16x32_bf16 v[88:91], v[60:63], v[12:15], v[88:91]
	s_waitcnt lgkmcnt(7)
	v_mfma_f32_16x16x32_bf16 v[80:83], v[48:51], v[0:3], v[224:227]
	v_mfma_f32_16x16x32_bf16 v[92:95], v[48:51], v[8:11], v[228:231]
	s_waitcnt lgkmcnt(6)
	v_mfma_f32_16x16x32_bf16 v[80:83], v[52:55], v[4:7], v[80:83]
	v_mfma_f32_16x16x32_bf16 v[92:95], v[52:55], v[12:15], v[92:95]
	s_waitcnt lgkmcnt(5)
	v_mfma_f32_16x16x32_bf16 v[96:99], v[40:43], v[0:3], v[224:227]
	v_mfma_f32_16x16x32_bf16 v[164:167], v[40:43], v[8:11], v[228:231]
	s_waitcnt lgkmcnt(4)
	v_mfma_f32_16x16x32_bf16 v[96:99], v[44:47], v[4:7], v[96:99]
	v_mfma_f32_16x16x32_bf16 v[164:167], v[44:47], v[12:15], v[164:167]
	s_waitcnt lgkmcnt(0)
	v_fmamk_f32 v72, v72, 0x3e38aa3b, v36
	v_fmamk_f32 v73, v73, 0x3e38aa3b, v37
	v_fmamk_f32 v74, v74, 0x3e38aa3b, v38
	v_fmamk_f32 v75, v75, 0x3e38aa3b, v39
	v_fmamk_f32 v84, v84, 0x3e38aa3b, v36
	v_fmamk_f32 v85, v85, 0x3e38aa3b, v37
	v_fmamk_f32 v86, v86, 0x3e38aa3b, v38
	v_fmamk_f32 v87, v87, 0x3e38aa3b, v39
	v_fmamk_f32 v76, v76, 0x3e38aa3b, v32
	v_fmamk_f32 v77, v77, 0x3e38aa3b, v33
	v_fmamk_f32 v78, v78, 0x3e38aa3b, v34
	v_fmamk_f32 v79, v79, 0x3e38aa3b, v35
	v_fmamk_f32 v88, v88, 0x3e38aa3b, v32
	v_fmamk_f32 v89, v89, 0x3e38aa3b, v33
	v_fmamk_f32 v90, v90, 0x3e38aa3b, v34
	v_fmamk_f32 v91, v91, 0x3e38aa3b, v35
	v_fmamk_f32 v80, v80, 0x3e38aa3b, v28
	v_fmamk_f32 v81, v81, 0x3e38aa3b, v29
	v_fmamk_f32 v82, v82, 0x3e38aa3b, v30
	v_fmamk_f32 v83, v83, 0x3e38aa3b, v31
	v_fmamk_f32 v92, v92, 0x3e38aa3b, v28
	v_fmamk_f32 v93, v93, 0x3e38aa3b, v29
	v_fmamk_f32 v94, v94, 0x3e38aa3b, v30
	v_fmamk_f32 v95, v95, 0x3e38aa3b, v31
	v_fmamk_f32 v96, v96, 0x3e38aa3b, v24
	v_fmamk_f32 v97, v97, 0x3e38aa3b, v25
	v_fmamk_f32 v98, v98, 0x3e38aa3b, v26
	v_fmamk_f32 v99, v99, 0x3e38aa3b, v27
	v_fmamk_f32 v164, v164, 0x3e38aa3b, v24
	v_fmamk_f32 v165, v165, 0x3e38aa3b, v25
	v_fmamk_f32 v166, v166, 0x3e38aa3b, v26
	v_fmamk_f32 v167, v167, 0x3e38aa3b, v27
	v_max3_f32 v146, v72, v73, v74
	v_max3_f32 v147, v80, v81, v82
	v_max3_f32 v146, v146, v75, v84
	v_max3_f32 v147, v147, v83, v92
	v_max3_f32 v146, v146, v85, v86
	v_max3_f32 v147, v147, v93, v94
	v_max3_f32 v146, v146, v87, v76
	v_max3_f32 v147, v147, v95, v96
	v_max3_f32 v146, v146, v77, v78
	v_max3_f32 v147, v147, v97, v98
	v_max3_f32 v146, v146, v79, v88
	v_max3_f32 v147, v147, v99, v164
	v_max3_f32 v146, v146, v89, v90
	v_max3_f32 v147, v147, v165, v166
	v_max3_f32 v146, v146, v91, v91
	v_max3_f32 v147, v147, v167, v167
	v_max_f32_e32 v146, v146, v147
	v_cmp_lt_f32_e32 vcc, 0x41000000, v146
	s_cbranch_vccnz .Lfox1_slow
; DI unsigned pk2(float lo, float hi) { unsigned r; asm volatile("v_cvt_pk_bf16_f32 %0, %1, %2" : "=v"(r) : "v"(lo), "v"(hi)); return r; }
; DI float ex2(float x) { return __builtin_amdgcn_exp2f(x); }
; DI f32x4 mmaT(bf16x8 a_m, bf16x8 b_n, f32x4 c) { return __builtin_amdgcn_mfma_f32_16x16x32_bf16(b_n, a_m, c, 0, 0, 0); }
; template <bool DIAG>
; DI void fox_tile(const bf16_t* sK, const bf16_t* sV, const float* sFk, const bf16x8 (&qf)[2][2], f32x4 (&o)[2][4], float (&mrun)[2], float (&lsum)[2], int key0, int qg0, int fr, int fq, int lane) {
;     ...
; #pragma unroll
;     for (int t = 0; t < 4; ++t)
; #pragma unroll
;       for (int j = 0; j < 4; ++j) { const float pv = ex2(s[mi][t][j] - mnew); s[mi][t][j] = pv; ps += pv; }
;     lsum[mi] = lsum[mi] * alpha + ps;
; #pragma unroll
;     for (int d = 0; d < 4; ++d) o[mi][d] *= alpha;
;   }
; #pragma unroll
;   for (int k2 = 0; k2 < 2; ++k2) {
;     bf16x8 pa[2];
; #pragma unroll
;     for (int mi = 0; mi < 2; ++mi) pa[mi] = mk8(pk2(s[mi][2 * k2][0], s[mi][2 * k2][1]), pk2(s[mi][2 * k2][2], s[mi][2 * k2][3]), pk2(s[mi][2 * k2 + 1][0], s[mi][2 * k2 + 1][1]), pk2(s[mi][2 * k2 + 1][2], s[mi][2 * k2 + 1][3]));
; #pragma unroll
;     for (int d = 0; d < 4; ++d) {
; #pragma unroll
;       for (int mi = 0; mi < 2; ++mi) o[mi][d] = mmaT(pa[mi], vf[k2][d], o[mi][d]);
;     }
	ds_read_b64_tr_b16 v[68:69], v221 offset:9216
	ds_read_b64_tr_b16 v[60:61], v221 offset:9248
	ds_read_b64_tr_b16 v[64:65], v221 offset:9280
	ds_read_b64_tr_b16 v[56:57], v221 offset:9312
	ds_read_b64_tr_b16 v[70:71], v221 offset:11520
	ds_read_b64_tr_b16 v[62:63], v221 offset:11552
	ds_read_b64_tr_b16 v[66:67], v221 offset:11584
	ds_read_b64_tr_b16 v[58:59], v221 offset:11616
	ds_read_b64_tr_b16 v[52:53], v221 offset:13824
	ds_read_b64_tr_b16 v[48:49], v221 offset:13856
	ds_read_b64_tr_b16 v[44:45], v221 offset:13888
	ds_read_b64_tr_b16 v[40:41], v221 offset:13920
	ds_read_b64_tr_b16 v[54:55], v221 offset:16128
	ds_read_b64_tr_b16 v[50:51], v221 offset:16160
	ds_read_b64_tr_b16 v[46:47], v221 offset:16192
	ds_read_b64_tr_b16 v[42:43], v221 offset:16224
	v_exp_f32_e32 v72, v72
	v_exp_f32_e32 v73, v73
	v_exp_f32_e32 v74, v74
	v_exp_f32_e32 v75, v75
	v_exp_f32_e32 v76, v76
	v_exp_f32_e32 v77, v77
	v_exp_f32_e32 v78, v78
	v_exp_f32_e32 v79, v79
	v_exp_f32_e32 v80, v80
	v_exp_f32_e32 v81, v81
	v_exp_f32_e32 v82, v82
	v_exp_f32_e32 v83, v83
	v_exp_f32_e32 v96, v96
	v_exp_f32_e32 v97, v97
	v_exp_f32_e32 v98, v98
	v_exp_f32_e32 v99, v99
	v_add_f32_e32 v146, v72, v73
	v_add_f32_e32 v147, v74, v75
	v_add_f32_e32 v148, v76, v77
	v_add_f32_e32 v149, v78, v79
	v_add_f32_e32 v150, v80, v81
	v_add_f32_e32 v151, v82, v83
	v_add_f32_e32 v152, v96, v97
	v_add_f32_e32 v153, v98, v99
	v_add_f32_e32 v146, v146, v147
	v_add_f32_e32 v147, v148, v149
	v_add_f32_e32 v148, v150, v151
	v_add_f32_e32 v149, v152, v153
	v_add_f32_e32 v146, v146, v147
	v_add_f32_e32 v148, v148, v149
	v_add_f32_e32 v146, v146, v148
	v_add_f32_e32 v128, v128, v146
	v_cvt_pk_bf16_f32 v36, v72, v73
	v_cvt_pk_bf16_f32 v37, v74, v75
	v_cvt_pk_bf16_f32 v38, v76, v77
	v_cvt_pk_bf16_f32 v39, v78, v79
	v_cvt_pk_bf16_f32 v28, v80, v81
	v_cvt_pk_bf16_f32 v29, v82, v83
	v_cvt_pk_bf16_f32 v30, v96, v97
	v_cvt_pk_bf16_f32 v31, v98, v99
	s_waitcnt lgkmcnt(8)
	v_mfma_f32_16x16x32_bf16 v[142:145], v[68:71], v[36:39], v[142:145]
	v_exp_f32_e32 v84, v84
	v_exp_f32_e32 v85, v85
	v_mfma_f32_16x16x32_bf16 v[138:141], v[60:63], v[36:39], v[138:141]
	v_exp_f32_e32 v86, v86
	v_exp_f32_e32 v87, v87
	v_mfma_f32_16x16x32_bf16 v[134:137], v[64:67], v[36:39], v[134:137]
	v_exp_f32_e32 v88, v88
	v_exp_f32_e32 v89, v89
	v_mfma_f32_16x16x32_bf16 v[130:133], v[56:59], v[36:39], v[130:133]
	v_exp_f32_e32 v90, v90
	v_exp_f32_e32 v91, v91
	s_waitcnt lgkmcnt(0)
	v_mfma_f32_16x16x32_bf16 v[142:145], v[52:55], v[28:31], v[142:145]
	v_exp_f32_e32 v92, v92
	v_exp_f32_e32 v93, v93
	v_mfma_f32_16x16x32_bf16 v[138:141], v[48:51], v[28:31], v[138:141]
	v_exp_f32_e32 v94, v94
	v_exp_f32_e32 v95, v95
	v_mfma_f32_16x16x32_bf16 v[134:137], v[44:47], v[28:31], v[134:137]
	v_exp_f32_e32 v164, v164
	v_exp_f32_e32 v165, v165
	v_mfma_f32_16x16x32_bf16 v[130:133], v[40:43], v[28:31], v[130:133]
	v_exp_f32_e32 v166, v166
	v_exp_f32_e32 v167, v167
	v_add_f32_e32 v146, v84, v85
	v_add_f32_e32 v147, v86, v87
	v_add_f32_e32 v148, v88, v89
	v_add_f32_e32 v149, v90, v91
	v_add_f32_e32 v150, v92, v93
	v_add_f32_e32 v151, v94, v95
	v_add_f32_e32 v152, v164, v165
	v_add_f32_e32 v153, v166, v167
	v_add_f32_e32 v146, v146, v147
	v_add_f32_e32 v147, v148, v149
	v_add_f32_e32 v148, v150, v151
	v_add_f32_e32 v149, v152, v153
	v_add_f32_e32 v146, v146, v147
	v_add_f32_e32 v148, v148, v149
	v_add_f32_e32 v146, v146, v148
	v_add_f32_e32 v129, v129, v146
	v_cvt_pk_bf16_f32 v32, v84, v85
	v_cvt_pk_bf16_f32 v33, v86, v87
	v_cvt_pk_bf16_f32 v34, v88, v89
	v_cvt_pk_bf16_f32 v35, v90, v91
	v_cvt_pk_bf16_f32 v24, v92, v93
	v_cvt_pk_bf16_f32 v25, v94, v95
	v_cvt_pk_bf16_f32 v26, v164, v165
	v_cvt_pk_bf16_f32 v27, v166, v167
	s_nop 1
	v_mfma_f32_16x16x32_bf16 v[122:125], v[68:71], v[32:35], v[122:125]
	v_mfma_f32_16x16x32_bf16 v[118:121], v[60:63], v[32:35], v[118:121]
	v_mfma_f32_16x16x32_bf16 v[114:117], v[64:67], v[32:35], v[114:117]
	v_mfma_f32_16x16x32_bf16 v[110:113], v[56:59], v[32:35], v[110:113]
	v_mfma_f32_16x16x32_bf16 v[122:125], v[52:55], v[24:27], v[122:125]
	v_mfma_f32_16x16x32_bf16 v[118:121], v[48:51], v[24:27], v[118:121]
	v_mfma_f32_16x16x32_bf16 v[114:117], v[44:47], v[24:27], v[114:117]
	v_mfma_f32_16x16x32_bf16 v[110:113], v[40:43], v[24:27], v[110:113]
	s_branch .Lfox1_join
; DI float ex2(float x) { return __builtin_amdgcn_exp2f(x); }
; DI f32x4 mmaT(bf16x8 a_m, bf16x8 b_n, f32x4 c) { return __builtin_amdgcn_mfma_f32_16x16x32_bf16(b_n, a_m, c, 0, 0, 0); }
; DI v4i16_t tr_rd(const bf16_t* a) { return __builtin_amdgcn_ds_read_tr16_b64_v4i16((LDSP v4i16_t*)a); }
; template <bool DIAG>
; DI void fox_tile(const bf16_t* sK, const bf16_t* sV, const float* sFk, const bf16x8 (&qf)[2][2], f32x4 (&o)[2][4], float (&mrun)[2], float (&lsum)[2], int key0, int qg0, int fr, int fq, int lane) {
;     ...
;   const int kof = (fr * 64 + fq * 16) ^ ((fr >> 3) << 5);
; #pragma unroll
;   for (int t = 0; t < 4; ++t) {
;     const bf16x8 k0 = *(const bf16x8*)((const unsigned char*)sK + (t * 2) * 1024 + kof), k1 = *(const bf16x8*)((const unsigned char*)sK + (t * 2 + 1) * 1024 + kof);
; #pragma unroll
;     for (int mi = 0; mi < 2; ++mi) { s[mi][t] = mmaT(qf[mi][0], k0, (f32x4){0.f, 0.f, 0.f, 0.f}); s[mi][t] = mmaT(qf[mi][1], k1, s[mi][t]); }
;   }
;   f32x4 fk[4];
; #pragma unroll
;   for (int t = 0; t < 4; ++t) fk[t] = *(const f32x4*)(sFk + 16 * t + 4 * fq);
;   __builtin_amdgcn_sched_barrier(0);
;   bf16x8 vf[2][4];
; #pragma unroll
;   for (int k2 = 0; k2 < 2; ++k2)
; #pragma unroll
;     for (int d = 0; d < 4; ++d) {
;       const bf16_t* a = sV + (32 * k2 + 4 * fq + (fr >> 2)) * 72 + 16 * d + 4 * (fr & 3);
;       const v4i16_t lo = tr_rd(a), hi = tr_rd(a + 16 * 72);
;       vf[k2][d] = __builtin_shufflevector(lo, hi, 0, 1, 2, 3, 4, 5, 6, 7);
;     }
;   __builtin_amdgcn_sched_barrier(0);
; #pragma unroll
;   for (int mi = 0; mi < 2; ++mi) {
;     float mx = -INFINITY;
; #pragma unroll
;     for (int t = 0; t < 4; ++t)
; #pragma unroll
;       for (int j = 0; j < 4; ++j) {
;         float x = __builtin_fmaf(s[mi][t][j], SC2, fk[t][j]);
;         if (DIAG) { if (key0 + 16 * t + 4 * fq + j > qg0 + 16 * mi) x = -INFINITY; }
;         s[mi][t][j] = x; mx = fmaxf(mx, x);
;       }
;     mx = fmaxf(mx, shx(mx, 16, lane)); mx = fmaxf(mx, shx(mx, 32, lane));
;     const float mnew = fmaxf(mrun[mi], mx), alpha = ex2(mrun[mi] - mnew);
;     mrun[mi] = mnew;
;     float ps = 0.f;
; #pragma unroll
;     for (int t = 0; t < 4; ++t)
; #pragma unroll
;       for (int j = 0; j < 4; ++j) { const float pv = ex2(s[mi][t][j] - mnew); s[mi][t][j] = pv; ps += pv; }
;     lsum[mi] = lsum[mi] * alpha + ps;
; #pragma unroll
;     for (int d = 0; d < 4; ++d) o[mi][d] *= alpha;
.Lfox1_slow:
	s_waitcnt lgkmcnt(11)
	v_mfma_f32_16x16x32_bf16 v[72:75], v[64:67], v[0:3], 0
	v_mfma_f32_16x16x32_bf16 v[64:67], v[64:67], v[8:11], 0
	s_waitcnt lgkmcnt(10)
	v_mfma_f32_16x16x32_bf16 v[84:87], v[68:71], v[12:15], v[64:67]
	s_waitcnt lgkmcnt(9)
	v_mfma_f32_16x16x32_bf16 v[64:67], v[56:59], v[0:3], 0
	v_mfma_f32_16x16x32_bf16 v[56:59], v[56:59], v[8:11], 0
	s_waitcnt lgkmcnt(8)
	v_mfma_f32_16x16x32_bf16 v[88:91], v[60:63], v[12:15], v[56:59]
	s_waitcnt lgkmcnt(7)
	v_mfma_f32_16x16x32_bf16 v[56:59], v[48:51], v[0:3], 0
	v_mfma_f32_16x16x32_bf16 v[48:51], v[48:51], v[8:11], 0
	s_waitcnt lgkmcnt(6)
	v_mfma_f32_16x16x32_bf16 v[92:95], v[52:55], v[12:15], v[48:51]
	s_waitcnt lgkmcnt(5)
	v_mfma_f32_16x16x32_bf16 v[48:51], v[40:43], v[0:3], 0
	v_mfma_f32_16x16x32_bf16 v[72:75], v[68:71], v[4:7], v[72:75]
	v_mfma_f32_16x16x32_bf16 v[76:79], v[60:63], v[4:7], v[64:67]
	v_mfma_f32_16x16x32_bf16 v[80:83], v[52:55], v[4:7], v[56:59]
	s_waitcnt lgkmcnt(4)
	v_mfma_f32_16x16x32_bf16 v[96:99], v[44:47], v[4:7], v[48:51]
	v_mfma_f32_16x16x32_bf16 v[40:43], v[40:43], v[8:11], 0
	v_mfma_f32_16x16x32_bf16 v[164:167], v[44:47], v[12:15], v[40:43]
	ds_read_b64_tr_b16 v[68:69], v221 offset:9216
	ds_read_b64_tr_b16 v[60:61], v221 offset:9248
	ds_read_b64_tr_b16 v[64:65], v221 offset:9280
	ds_read_b64_tr_b16 v[56:57], v221 offset:9312
	ds_read_b64_tr_b16 v[70:71], v221 offset:11520
	ds_read_b64_tr_b16 v[62:63], v221 offset:11552
	ds_read_b64_tr_b16 v[66:67], v221 offset:11584
	ds_read_b64_tr_b16 v[58:59], v221 offset:11616
	ds_read_b64_tr_b16 v[52:53], v221 offset:13824
	ds_read_b64_tr_b16 v[48:49], v221 offset:13856
	ds_read_b64_tr_b16 v[44:45], v221 offset:13888
	ds_read_b64_tr_b16 v[40:41], v221 offset:13920
	ds_read_b64_tr_b16 v[54:55], v221 offset:16128
	ds_read_b64_tr_b16 v[50:51], v221 offset:16160
	ds_read_b64_tr_b16 v[46:47], v221 offset:16192
	ds_read_b64_tr_b16 v[42:43], v221 offset:16224
	s_waitcnt lgkmcnt(14)
	v_fmamk_f32 v72, v72, 0x3e38aa3b, v36
	v_fmamk_f32 v73, v73, 0x3e38aa3b, v37
	s_mov_b32 s4, 0xff800000
	v_max3_f32 v100, v72, s4, v73
	v_fmamk_f32 v74, v74, 0x3e38aa3b, v38
	v_fmamk_f32 v75, v75, 0x3e38aa3b, v39
	v_max3_f32 v100, v100, v74, v75
	v_fmamk_f32 v101, v76, 0x3e38aa3b, v32
	v_fmamk_f32 v77, v77, 0x3e38aa3b, v33
	v_max3_f32 v76, v100, v101, v77
	v_fmamk_f32 v100, v78, 0x3e38aa3b, v34
	v_fmamk_f32 v79, v79, 0x3e38aa3b, v35
	v_max3_f32 v76, v76, v100, v79
	v_fmamk_f32 v102, v80, 0x3e38aa3b, v28
	v_fmamk_f32 v81, v81, 0x3e38aa3b, v29
	v_max3_f32 v76, v76, v102, v81
	v_fmamk_f32 v103, v82, 0x3e38aa3b, v30
	v_fmamk_f32 v83, v83, 0x3e38aa3b, v31
	v_max3_f32 v76, v76, v103, v83
	v_fmamk_f32 v96, v96, 0x3e38aa3b, v24
	v_fmamk_f32 v97, v97, 0x3e38aa3b, v25
	v_max3_f32 v76, v76, v96, v97
	v_fmamk_f32 v98, v98, 0x3e38aa3b, v26
	v_fmamk_f32 v99, v99, 0x3e38aa3b, v27
	v_max3_f32 v76, v76, v98, v99
	ds_bpermute_b32 v78, v204, v76
	v_fmamk_f32 v36, v84, 0x3e38aa3b, v36
	v_fmamk_f32 v37, v85, 0x3e38aa3b, v37
	v_fmamk_f32 v38, v86, 0x3e38aa3b, v38
	v_fmac_f32_e32 v39, 0x3e38aa3b, v87
	s_waitcnt lgkmcnt(0)
	v_max_f32_e32 v78, v78, v78
	v_max_f32_e32 v76, v76, v78
	ds_bpermute_b32 v78, v169, v76
	v_fmamk_f32 v32, v88, 0x3e38aa3b, v32
	v_fmamk_f32 v33, v89, 0x3e38aa3b, v33
	v_fmamk_f32 v34, v90, 0x3e38aa3b, v34
	v_fmac_f32_e32 v35, 0x3e38aa3b, v91
	s_waitcnt lgkmcnt(0)
	v_max3_f32 v220, v219, v76, v78
	v_sub_f32_e32 v73, v73, v220
	v_exp_f32_e32 v76, v73
	v_sub_f32_e32 v73, v74, v220
	v_exp_f32_e32 v74, v73
	v_sub_f32_e32 v73, v75, v220
	v_exp_f32_e32 v78, v73
	v_sub_f32_e32 v73, v101, v220
	v_exp_f32_e32 v82, v73
	v_sub_f32_e32 v73, v77, v220
	v_exp_f32_e32 v80, v73
	v_sub_f32_e32 v73, v100, v220
	v_exp_f32_e32 v100, v73
	v_sub_f32_e32 v73, v79, v220
	v_exp_f32_e32 v104, v73
	v_sub_f32_e32 v73, v102, v220
	v_exp_f32_e32 v102, v73
	v_sub_f32_e32 v73, v81, v220
	v_exp_f32_e32 v106, v73
	v_sub_f32_e32 v73, v103, v220
	v_exp_f32_e32 v148, v73
	v_sub_f32_e32 v73, v83, v220
	v_exp_f32_e32 v146, v73
	v_sub_f32_e32 v73, v96, v220
	v_exp_f32_e32 v150, v73
	v_sub_f32_e32 v73, v97, v220
	v_exp_f32_e32 v154, v73
	v_sub_f32_e32 v73, v98, v220
	v_exp_f32_e32 v152, v73
	v_sub_f32_e32 v73, v99, v220
	v_exp_f32_e32 v158, v73
	v_max3_f32 v73, v36, s4, v37
	v_max3_f32 v73, v73, v38, v39
	v_max3_f32 v73, v73, v32, v33
	v_max3_f32 v73, v73, v34, v35
	v_fmamk_f32 v28, v92, 0x3e38aa3b, v28
	v_fmamk_f32 v29, v93, 0x3e38aa3b, v29
	v_max3_f32 v73, v73, v28, v29
	v_fmamk_f32 v30, v94, 0x3e38aa3b, v30
	v_fmac_f32_e32 v31, 0x3e38aa3b, v95
	v_max3_f32 v73, v73, v30, v31
	v_fmamk_f32 v24, v164, 0x3e38aa3b, v24
	v_fmamk_f32 v25, v165, 0x3e38aa3b, v25
	v_max3_f32 v73, v73, v24, v25
	v_fmamk_f32 v26, v166, 0x3e38aa3b, v26
	v_fmac_f32_e32 v27, 0x3e38aa3b, v167
	v_max3_f32 v73, v73, v26, v27
	ds_bpermute_b32 v75, v204, v73
	v_sub_f32_e32 v105, v219, v220
	v_exp_f32_e32 v156, v105
	v_sub_f32_e32 v72, v72, v220
	v_exp_f32_e32 v72, v72
	s_waitcnt lgkmcnt(0)
	v_max_f32_e32 v75, v75, v75
	v_max_f32_e32 v73, v73, v75
	ds_bpermute_b32 v75, v169, v73
	v_pk_mul_f32 v[86:87], v[144:145], v[156:157] op_sel_hi:[1,0]
	v_pk_mul_f32 v[84:85], v[142:143], v[156:157] op_sel_hi:[1,0]
	v_pk_mul_f32 v[90:91], v[140:141], v[156:157] op_sel_hi:[1,0]
	v_pk_mul_f32 v[88:89], v[138:139], v[156:157] op_sel_hi:[1,0]
	s_waitcnt lgkmcnt(0)
; DI unsigned pk2(float lo, float hi) { unsigned r; asm volatile("v_cvt_pk_bf16_f32 %0, %1, %2" : "=v"(r) : "v"(lo), "v"(hi)); return r; }
; DI float ex2(float x) { return __builtin_amdgcn_exp2f(x); }
; DI f32x4 mmaT(bf16x8 a_m, bf16x8 b_n, f32x4 c) { return __builtin_amdgcn_mfma_f32_16x16x32_bf16(b_n, a_m, c, 0, 0, 0); }
; template <bool DIAG>
; DI void fox_tile(const bf16_t* sK, const bf16_t* sV, const float* sFk, const bf16x8 (&qf)[2][2], f32x4 (&o)[2][4], float (&mrun)[2], float (&lsum)[2], int key0, int qg0, int fr, int fq, int lane) {
;     ...
;     const float mnew = fmaxf(mrun[mi], mx), alpha = ex2(mrun[mi] - mnew);
;     mrun[mi] = mnew;
;     float ps = 0.f;
; #pragma unroll
;     for (int t = 0; t < 4; ++t)
; #pragma unroll
;       for (int j = 0; j < 4; ++j) { const float pv = ex2(s[mi][t][j] - mnew); s[mi][t][j] = pv; ps += pv; }
;     lsum[mi] = lsum[mi] * alpha + ps;
; #pragma unroll
;     for (int d = 0; d < 4; ++d) o[mi][d] *= alpha;
;   }
; #pragma unroll
;   for (int k2 = 0; k2 < 2; ++k2) {
;     bf16x8 pa[2];
; #pragma unroll
;     for (int mi = 0; mi < 2; ++mi) pa[mi] = mk8(pk2(s[mi][2 * k2][0], s[mi][2 * k2][1]), pk2(s[mi][2 * k2][2], s[mi][2 * k2][3]), pk2(s[mi][2 * k2 + 1][0], s[mi][2 * k2 + 1][1]), pk2(s[mi][2 * k2 + 1][2], s[mi][2 * k2 + 1][3]));
; #pragma unroll
;     for (int d = 0; d < 4; ++d) {
; #pragma unroll
;       for (int mi = 0; mi < 2; ++mi) o[mi][d] = mmaT(pa[mi], vf[k2][d], o[mi][d]);
;     }
	v_max3_f32 v222, v218, v73, v75
	v_sub_f32_e32 v103, v218, v222
	v_pk_mul_f32 v[94:95], v[136:137], v[156:157] op_sel_hi:[1,0]
	v_pk_mul_f32 v[92:93], v[134:135], v[156:157] op_sel_hi:[1,0]
	v_pk_mul_f32 v[98:99], v[132:133], v[156:157] op_sel_hi:[1,0]
	v_pk_mul_f32 v[96:97], v[130:131], v[156:157] op_sel_hi:[1,0]
	v_exp_f32_e32 v157, v103
	v_sub_f32_e32 v32, v32, v222
	v_sub_f32_e32 v36, v36, v222
	v_exp_f32_e32 v83, v32
	v_sub_f32_e32 v32, v33, v222
	v_exp_f32_e32 v73, v36
	v_sub_f32_e32 v36, v37, v222
	v_exp_f32_e32 v81, v32
	v_sub_f32_e32 v32, v34, v222
	v_exp_f32_e32 v77, v36
	v_sub_f32_e32 v36, v38, v222
	v_exp_f32_e32 v101, v32
	v_sub_f32_e32 v32, v35, v222
	v_mov_b32_e32 v130, v157
	v_exp_f32_e32 v75, v36
	v_sub_f32_e32 v36, v39, v222
	v_exp_f32_e32 v105, v32
	v_sub_f32_e32 v28, v28, v222
	v_pk_mul_f32 v[34:35], v[124:125], v[130:131] op_sel_hi:[1,0]
	v_pk_mul_f32 v[32:33], v[122:123], v[130:131] op_sel_hi:[1,0]
	v_exp_f32_e32 v79, v36
	v_exp_f32_e32 v103, v28
	v_sub_f32_e32 v28, v29, v222
	v_cvt_pk_bf16_f32 v36, v72, v76
	v_cvt_pk_bf16_f32 v37, v74, v78
	v_cvt_pk_bf16_f32 v38, v82, v80
	v_cvt_pk_bf16_f32 v39, v100, v104
	v_cvt_pk_bf16_f32 v122, v73, v77
	v_cvt_pk_bf16_f32 v123, v75, v79
	v_cvt_pk_bf16_f32 v124, v83, v81
	v_cvt_pk_bf16_f32 v125, v101, v105
	v_sub_f32_e32 v24, v24, v222
	v_mfma_f32_16x16x32_bf16 v[32:35], v[68:71], v[122:125], v[32:35]
	v_exp_f32_e32 v107, v28
	v_sub_f32_e32 v28, v30, v222
	v_exp_f32_e32 v151, v24
	v_mfma_f32_16x16x32_bf16 v[84:87], v[68:71], v[36:39], v[84:87]
	v_sub_f32_e32 v68, v31, v222
	v_sub_f32_e32 v24, v25, v222
	v_exp_f32_e32 v149, v28
	v_mfma_f32_16x16x32_bf16 v[28:31], v[60:63], v[36:39], v[88:91]
	v_exp_f32_e32 v147, v68
	v_pk_mul_f32 v[70:71], v[120:121], v[130:131] op_sel_hi:[1,0]
	v_pk_mul_f32 v[68:69], v[118:119], v[130:131] op_sel_hi:[1,0]
	v_exp_f32_e32 v155, v24
	v_pk_mul_f32 v[90:91], v[116:117], v[130:131] op_sel_hi:[1,0]
	v_pk_mul_f32 v[88:89], v[114:115], v[130:131] op_sel_hi:[1,0]
	v_sub_f32_e32 v24, v26, v222
	v_mfma_f32_16x16x32_bf16 v[60:63], v[60:63], v[122:125], v[68:71]
	v_exp_f32_e32 v153, v24
	v_mfma_f32_16x16x32_bf16 v[68:71], v[64:67], v[36:39], v[92:95]
	v_mfma_f32_16x16x32_bf16 v[64:67], v[64:67], v[122:125], v[88:91]
	s_nop 2
	v_sub_f32_e32 v88, v27, v222
	v_mfma_f32_16x16x32_bf16 v[24:27], v[56:59], v[36:39], v[96:99]
	v_mul_f32_e64 v38, v112, v130
	v_mul_f32_e64 v39, v113, v130
	v_pk_mul_f32 v[36:37], v[110:111], v[130:131] op_sel_hi:[1,0]
	v_exp_f32_e32 v159, v88
	s_nop 0
	v_mfma_f32_16x16x32_bf16 v[36:39], v[56:59], v[122:125], v[36:39]
	v_cvt_pk_bf16_f32 v56, v102, v106
	v_cvt_pk_bf16_f32 v57, v148, v146
	v_cvt_pk_bf16_f32 v58, v150, v154
	v_cvt_pk_bf16_f32 v59, v152, v158
	v_cvt_pk_bf16_f32 v110, v103, v107
	v_cvt_pk_bf16_f32 v111, v149, v147
	v_cvt_pk_bf16_f32 v112, v151, v155
	v_cvt_pk_bf16_f32 v113, v153, v159
	s_nop 0
	v_mfma_f32_16x16x32_bf16 v[92:95], v[52:55], v[110:113], v[32:35]
	s_nop 2
	v_add_f32_e64 v32, v72, 0
	v_add_f32_e64 v33, v73, 0
	v_mfma_f32_16x16x32_bf16 v[88:91], v[52:55], v[56:59], v[84:87]
	v_add_f32_e64 v32, v76, v32
	v_add_f32_e64 v33, v77, v33
	v_mfma_f32_16x16x32_bf16 v[84:87], v[48:51], v[56:59], v[28:31]
	s_nop 2
	v_add_f32_e64 v28, v74, v32
	v_add_f32_e64 v29, v75, v33
	v_mfma_f32_16x16x32_bf16 v[96:99], v[48:51], v[110:113], v[60:63]
	v_add_f32_e64 v28, v78, v28
	v_add_f32_e64 v29, v79, v29
	v_pk_add_f32 v[28:29], v[82:83], v[28:29]
	v_mfma_f32_16x16x32_bf16 v[76:79], v[40:43], v[56:59], v[24:27]
	v_add_f32_e64 v28, v80, v28
	v_add_f32_e64 v29, v81, v29
	v_pk_add_f32 v[28:29], v[100:101], v[28:29]
	v_mfma_f32_16x16x32_bf16 v[80:83], v[44:47], v[56:59], v[68:71]
	v_add_f32_e64 v28, v104, v28
	v_add_f32_e64 v29, v105, v29
	v_pk_add_f32 v[28:29], v[102:103], v[28:29]
	v_mfma_f32_16x16x32_bf16 v[100:103], v[44:47], v[110:113], v[64:67]
	v_add_f32_e64 v28, v106, v28
	v_add_f32_e64 v29, v107, v29
	v_pk_add_f32 v[28:29], v[148:149], v[28:29]
	v_mfma_f32_16x16x32_bf16 v[72:75], v[40:43], v[110:113], v[36:39]
	v_add_f32_e64 v28, v146, v28
	v_add_f32_e64 v29, v147, v29
	v_pk_add_f32 v[28:29], v[150:151], v[28:29]
	s_nop 0
	v_pk_add_f32 v[28:29], v[154:155], v[28:29]
	s_nop 0
	v_pk_add_f32 v[24:25], v[152:153], v[28:29]
	s_nop 0
	v_pk_add_f32 v[24:25], v[158:159], v[24:25]
	s_nop 0
	v_pk_fma_f32 v[104:105], v[128:129], v[156:157], v[24:25]
	v_mul_f32_e32 v224, 0xc0b17218, v220
	v_mul_f32_e32 v228, 0xc0b17218, v222
	v_mov_b32_e32 v225, v224
	v_mov_b32_e32 v229, v228
	v_mov_b32_e32 v226, v224
	v_mov_b32_e32 v230, v228
	v_mov_b32_e32 v227, v224
	v_mov_b32_e32 v231, v228
.LBB0_493:
	s_nop 3
	v_mov_b32_e32 v110, v72
	v_mov_b32_e32 v111, v73
	v_mov_b32_e32 v112, v74
	v_mov_b32_e32 v113, v75
	v_mov_b32_e32 v114, v100
	v_mov_b32_e32 v115, v101
	v_mov_b32_e32 v116, v102
	v_mov_b32_e32 v117, v103
	v_mov_b32_e32 v118, v96
	v_mov_b32_e32 v119, v97
	v_mov_b32_e32 v120, v98
	v_mov_b32_e32 v121, v99
	v_mov_b32_e32 v122, v92
	v_mov_b32_e32 v123, v93
	v_mov_b32_e32 v124, v94
	v_mov_b32_e32 v125, v95
	v_mov_b32_e32 v130, v76
	v_mov_b32_e32 v131, v77
	v_mov_b32_e32 v132, v78
	v_mov_b32_e32 v133, v79
	v_mov_b32_e32 v134, v80
	v_mov_b32_e32 v135, v81
	v_mov_b32_e32 v136, v82
	v_mov_b32_e32 v137, v83
	v_mov_b32_e32 v138, v84
	v_mov_b32_e32 v139, v85
	v_mov_b32_e32 v140, v86
	v_mov_b32_e32 v141, v87
	v_mov_b32_e32 v142, v88
	v_mov_b32_e32 v143, v89
	v_mov_b32_e32 v144, v90
	v_mov_b32_e32 v145, v91
	v_mov_b32_e32 v219, v220
	v_mov_b32_e32 v218, v222
	v_mov_b32_e32 v128, v104
	v_mov_b32_e32 v129, v105
.Lfox1_join:
	s_or_b64 exec, exec, s[14:15]
	s_andn2_b64 vcc, exec, s[12:13]
	s_cbranch_vccnz .LBB0_497

; DI f32x4 mmaT(bf16x8 a_m, bf16x8 b_n, f32x4 c) { return __builtin_amdgcn_mfma_f32_16x16x32_bf16(b_n, a_m, c, 0, 0, 0); }
; DI v4i16_t tr_rd(const bf16_t* a) { return __builtin_amdgcn_ds_read_tr16_b64_v4i16((LDSP v4i16_t*)a); }
; DI float shx(float v, int m, int lane) { return __int_as_float(__builtin_amdgcn_ds_bpermute((lane ^ m) << 2, __float_as_int(v))); }
; template <bool DIAG>
; DI void fox_tile(const bf16_t* sK, const bf16_t* sV, const float* sFk, const bf16x8 (&qf)[2][2], f32x4 (&o)[2][4], float (&mrun)[2], float (&lsum)[2], int key0, int qg0, int fr, int fq, int lane) {
;     ...
;   const int kof = (fr * 64 + fq * 16) ^ ((fr >> 3) << 5);
; #pragma unroll
;   for (int t = 0; t < 4; ++t) {
;     const bf16x8 k0 = *(const bf16x8*)((const unsigned char*)sK + (t * 2) * 1024 + kof), k1 = *(const bf16x8*)((const unsigned char*)sK + (t * 2 + 1) * 1024 + kof);
; #pragma unroll
;     for (int mi = 0; mi < 2; ++mi) { s[mi][t] = mmaT(qf[mi][0], k0, (f32x4){0.f, 0.f, 0.f, 0.f}); s[mi][t] = mmaT(qf[mi][1], k1, s[mi][t]); }
;   }
;   f32x4 fk[4];
; #pragma unroll
;   for (int t = 0; t < 4; ++t) fk[t] = *(const f32x4*)(sFk + 16 * t + 4 * fq);
;   __builtin_amdgcn_sched_barrier(0);
;   bf16x8 vf[2][4];
; #pragma unroll
;   for (int k2 = 0; k2 < 2; ++k2)
; #pragma unroll
;     for (int d = 0; d < 4; ++d) {
;       const bf16_t* a = sV + (32 * k2 + 4 * fq + (fr >> 2)) * 72 + 16 * d + 4 * (fr & 3);
;       const v4i16_t lo = tr_rd(a), hi = tr_rd(a + 16 * 72);
;       vf[k2][d] = __builtin_shufflevector(lo, hi, 0, 1, 2, 3, 4, 5, 6, 7);
;     }
;   __builtin_amdgcn_sched_barrier(0);
; #pragma unroll
;   for (int mi = 0; mi < 2; ++mi) {
;     float mx = -INFINITY;
; #pragma unroll
;     for (int t = 0; t < 4; ++t)
; #pragma unroll
;       for (int j = 0; j < 4; ++j) {
;         float x = __builtin_fmaf(s[mi][t][j], SC2, fk[t][j]);
;         if (DIAG) { if (key0 + 16 * t + 4 * fq + j > qg0 + 16 * mi) x = -INFINITY; }
;         s[mi][t][j] = x; mx = fmaxf(mx, x);
;       }
;     mx = fmaxf(mx, shx(mx, 16, lane)); mx = fmaxf(mx, shx(mx, 32, lane));
.LBB0_609:
	s_mul_i32 s4, s20, 0x4900
	s_add_i32 s4, s4, 32
	v_add_u32_e32 v24, s4, v213
	ds_read_b128 v[64:67], v24
	ds_read_b128 v[68:71], v24 offset:1024
	ds_read_b128 v[56:59], v24 offset:2048
	ds_read_b128 v[60:63], v24 offset:3072
	ds_read_b128 v[48:51], v24 offset:4096
	ds_read_b128 v[52:55], v24 offset:5120
	ds_read_b128 v[40:43], v24 offset:6144
	ds_read_b128 v[44:47], v24 offset:7168
	v_lshl_add_u32 v24, v209, 2, s4
	ds_read_b128 v[36:39], v24 offset:18432
	ds_read_b128 v[32:35], v24 offset:18496
	ds_read_b128 v[28:31], v24 offset:18560
	ds_read_b128 v[24:27], v24 offset:18624
	v_lshl_add_u32 v72, v214, 1, s4
	s_cmp_lt_i32 s21, s16
	s_mov_b64 s[4:5], -1
	v_add_u32_e32 v221, v72, v215
	s_cbranch_scc1 .LBB0_611
	s_waitcnt lgkmcnt(11)
	v_mfma_f32_16x16x32_bf16 v[72:75], v[64:67], v[0:3], 0
	s_waitcnt lgkmcnt(10)
	v_mfma_f32_16x16x32_bf16 v[146:149], v[68:71], v[4:7], v[72:75]
	v_mfma_f32_16x16x32_bf16 v[72:75], v[64:67], v[8:11], 0
	v_mfma_f32_16x16x32_bf16 v[222:225], v[68:71], v[12:15], v[72:75]
	s_waitcnt lgkmcnt(9)
	v_mfma_f32_16x16x32_bf16 v[72:75], v[56:59], v[0:3], 0
	s_waitcnt lgkmcnt(8)
	v_mfma_f32_16x16x32_bf16 v[150:153], v[60:63], v[4:7], v[72:75]
	v_mfma_f32_16x16x32_bf16 v[72:75], v[56:59], v[8:11], 0
	v_mfma_f32_16x16x32_bf16 v[226:229], v[60:63], v[12:15], v[72:75]
	s_waitcnt lgkmcnt(7)
	v_mfma_f32_16x16x32_bf16 v[72:75], v[48:51], v[0:3], 0
	s_waitcnt lgkmcnt(6)
	v_mfma_f32_16x16x32_bf16 v[154:157], v[52:55], v[4:7], v[72:75]
	v_mfma_f32_16x16x32_bf16 v[72:75], v[48:51], v[8:11], 0
	v_mfma_f32_16x16x32_bf16 v[230:233], v[52:55], v[12:15], v[72:75]
	s_waitcnt lgkmcnt(5)
	v_mfma_f32_16x16x32_bf16 v[72:75], v[40:43], v[0:3], 0
	s_waitcnt lgkmcnt(4)
	v_mfma_f32_16x16x32_bf16 v[172:175], v[44:47], v[4:7], v[72:75]
	v_mfma_f32_16x16x32_bf16 v[72:75], v[40:43], v[8:11], 0
	v_mfma_f32_16x16x32_bf16 v[104:107], v[44:47], v[12:15], v[72:75]
	ds_read_b64_tr_b16 v[100:101], v221 offset:9216
	ds_read_b64_tr_b16 v[92:93], v221 offset:9248
	ds_read_b64_tr_b16 v[96:97], v221 offset:9280
	ds_read_b64_tr_b16 v[88:89], v221 offset:9312
	ds_read_b64_tr_b16 v[102:103], v221 offset:11520
	ds_read_b64_tr_b16 v[94:95], v221 offset:11552
	ds_read_b64_tr_b16 v[98:99], v221 offset:11584
	ds_read_b64_tr_b16 v[90:91], v221 offset:11616
	ds_read_b64_tr_b16 v[84:85], v221 offset:13824
	ds_read_b64_tr_b16 v[80:81], v221 offset:13856
	ds_read_b64_tr_b16 v[76:77], v221 offset:13888
	ds_read_b64_tr_b16 v[72:73], v221 offset:13920
	ds_read_b64_tr_b16 v[86:87], v221 offset:16128
	ds_read_b64_tr_b16 v[82:83], v221 offset:16160
	ds_read_b64_tr_b16 v[78:79], v221 offset:16192
	ds_read_b64_tr_b16 v[74:75], v221 offset:16224
	v_add_u32_e32 v159, s17, v209
	s_waitcnt lgkmcnt(14)
	v_fmamk_f32 v147, v147, 0x3e38aa3b, v37
	v_cmp_lt_i32_e64 s[4:5], v159, v206
	v_add_u32_e32 v164, 2, v159
	v_fmamk_f32 v148, v148, 0x3e38aa3b, v38
	v_cndmask_b32_e64 v147, v200, v147, s[4:5]
	v_cmp_le_i32_e64 s[4:5], v164, v206
	v_add_u32_e32 v165, 3, v159
	v_fmamk_f32 v149, v149, 0x3e38aa3b, v39
	v_cndmask_b32_e64 v148, v200, v148, s[4:5]
	v_cmp_le_i32_e64 s[4:5], v165, v206
	v_add_u32_e32 v166, 16, v159
	v_fmamk_f32 v146, v146, 0x3e38aa3b, v36
	v_cmp_gt_i32_e32 vcc, v159, v206
	v_cndmask_b32_e64 v149, v200, v149, s[4:5]
	v_fmamk_f32 v150, v150, 0x3e38aa3b, v32
	v_cmp_le_i32_e64 s[4:5], v166, v206
	v_cndmask_b32_e32 v146, v146, v200, vcc
	s_mov_b32 s21, 0xff800000
	v_cndmask_b32_e64 v166, v200, v150, s[4:5]
	v_fmamk_f32 v150, v151, 0x3e38aa3b, v33
	v_add_u32_e32 v151, 17, v159
	v_max3_f32 v158, v146, s21, v147
	v_cmp_le_i32_e64 s[4:5], v151, v206
	v_add_u32_e32 v177, 18, v159
	v_max3_f32 v158, v158, v148, v149
	v_cndmask_b32_e64 v167, v200, v150, s[4:5]
	v_fmamk_f32 v152, v152, 0x3e38aa3b, v34
	v_cmp_le_i32_e64 s[4:5], v177, v206
	v_max3_f32 v150, v158, v166, v167
	v_add_u32_e32 v179, 32, v159
	v_cndmask_b32_e64 v158, v200, v152, s[4:5]
	v_fmamk_f32 v152, v153, 0x3e38aa3b, v35
	v_add_u32_e32 v153, 19, v159
	v_cmp_le_i32_e64 s[4:5], v153, v206
	v_add_u32_e32 v181, 34, v159
	v_add_u32_e32 v185, 48, v159
	v_cndmask_b32_e64 v176, v200, v152, s[4:5]
	v_fmamk_f32 v152, v154, 0x3e38aa3b, v28
	v_cmp_le_i32_e64 s[4:5], v179, v206
	v_add_u32_e32 v187, 50, v159
	v_max3_f32 v150, v150, v158, v176
	v_cndmask_b32_e64 v178, v200, v152, s[4:5]
	v_fmamk_f32 v152, v155, 0x3e38aa3b, v29
	v_add_u32_e32 v155, 33, v159
	v_cmp_le_i32_e64 s[4:5], v155, v206
	v_fmamk_f32 v104, v104, 0x3e38aa3b, v24
	s_nop 0
	v_cndmask_b32_e64 v180, v200, v152, s[4:5]
	v_fmamk_f32 v152, v156, 0x3e38aa3b, v30
	v_cmp_le_i32_e64 s[4:5], v181, v206
	v_max3_f32 v150, v150, v178, v180
	s_nop 0
	v_cndmask_b32_e64 v182, v200, v152, s[4:5]
	v_fmamk_f32 v152, v157, 0x3e38aa3b, v31
	v_add_u32_e32 v157, 35, v159
	v_cmp_le_i32_e64 s[4:5], v157, v206
	s_nop 1
	v_cndmask_b32_e64 v183, v200, v152, s[4:5]
	v_fmamk_f32 v152, v172, 0x3e38aa3b, v24
	v_cmp_le_i32_e64 s[4:5], v185, v206
	v_max3_f32 v150, v150, v182, v183
	s_nop 0
	v_cndmask_b32_e64 v184, v200, v152, s[4:5]
	v_fmamk_f32 v152, v173, 0x3e38aa3b, v25
	v_add_u32_e32 v173, 49, v159
	v_cmp_le_i32_e64 s[4:5], v173, v206
	s_nop 1
	v_cndmask_b32_e64 v186, v200, v152, s[4:5]
	v_fmamk_f32 v152, v174, 0x3e38aa3b, v26
	v_cmp_le_i32_e64 s[4:5], v187, v206
	v_max3_f32 v150, v150, v184, v186
	s_nop 0
	v_cndmask_b32_e64 v188, v200, v152, s[4:5]
	v_fmamk_f32 v152, v175, 0x3e38aa3b, v27
	v_add_u32_e32 v175, 51, v159
	v_cmp_le_i32_e64 s[4:5], v175, v206
	s_nop 1
	v_cndmask_b32_e64 v189, v200, v152, s[4:5]
	v_max3_f32 v150, v150, v188, v189
	ds_bpermute_b32 v152, v204, v150
	v_cmp_le_i32_e64 s[4:5], v159, v207
	s_waitcnt lgkmcnt(0)
	v_max_f32_e32 v152, v152, v152
	v_max_f32_e32 v150, v150, v152
	ds_bpermute_b32 v152, v169, v150
	s_waitcnt lgkmcnt(0)
; DI unsigned pk2(float lo, float hi) { unsigned r; asm volatile("v_cvt_pk_bf16_f32 %0, %1, %2" : "=v"(r) : "v"(lo), "v"(hi)); return r; }
; DI float ex2(float x) { return __builtin_amdgcn_exp2f(x); }
; DI f32x4 mmaT(bf16x8 a_m, bf16x8 b_n, f32x4 c) { return __builtin_amdgcn_mfma_f32_16x16x32_bf16(b_n, a_m, c, 0, 0, 0); }
; DI float shx(float v, int m, int lane) { return __int_as_float(__builtin_amdgcn_ds_bpermute((lane ^ m) << 2, __float_as_int(v))); }
; template <bool DIAG>
; DI void fox_tile(const bf16_t* sK, const bf16_t* sV, const float* sFk, const bf16x8 (&qf)[2][2], f32x4 (&o)[2][4], float (&mrun)[2], float (&lsum)[2], int key0, int qg0, int fr, int fq, int lane) {
;     ...
;     float mx = -INFINITY;
; #pragma unroll
;     for (int t = 0; t < 4; ++t)
; #pragma unroll
;       for (int j = 0; j < 4; ++j) {
;         float x = __builtin_fmaf(s[mi][t][j], SC2, fk[t][j]);
;         if (DIAG) { if (key0 + 16 * t + 4 * fq + j > qg0 + 16 * mi) x = -INFINITY; }
;         s[mi][t][j] = x; mx = fmaxf(mx, x);
;       }
;     mx = fmaxf(mx, shx(mx, 16, lane)); mx = fmaxf(mx, shx(mx, 32, lane));
;     const float mnew = fmaxf(mrun[mi], mx), alpha = ex2(mrun[mi] - mnew);
;     mrun[mi] = mnew;
;     float ps = 0.f;
; #pragma unroll
;     for (int t = 0; t < 4; ++t)
; #pragma unroll
;       for (int j = 0; j < 4; ++j) { const float pv = ex2(s[mi][t][j] - mnew); s[mi][t][j] = pv; ps += pv; }
;     lsum[mi] = lsum[mi] * alpha + ps;
; #pragma unroll
;     for (int d = 0; d < 4; ++d) o[mi][d] *= alpha;
;   }
; #pragma unroll
;   for (int k2 = 0; k2 < 2; ++k2) {
;     bf16x8 pa[2];
; #pragma unroll
;     for (int mi = 0; mi < 2; ++mi) pa[mi] = mk8(pk2(s[mi][2 * k2][0], s[mi][2 * k2][1]), pk2(s[mi][2 * k2][2], s[mi][2 * k2][3]), pk2(s[mi][2 * k2 + 1][0], s[mi][2 * k2 + 1][1]), pk2(s[mi][2 * k2 + 1][2], s[mi][2 * k2 + 1][3]));
; #pragma unroll
;     for (int d = 0; d < 4; ++d) {
; #pragma unroll
;       for (int mi = 0; mi < 2; ++mi) o[mi][d] = mmaT(pa[mi], vf[k2][d], o[mi][d]);
	v_max3_f32 v220, v219, v150, v152
	v_sub_f32_e32 v147, v147, v220
	v_exp_f32_e32 v150, v147
	v_sub_f32_e32 v147, v148, v220
	v_exp_f32_e32 v148, v147
	v_sub_f32_e32 v147, v149, v220
	v_exp_f32_e32 v152, v147
	v_sub_f32_e32 v147, v166, v220
	v_exp_f32_e32 v156, v147
	v_sub_f32_e32 v147, v167, v220
	v_exp_f32_e32 v154, v147
	v_sub_f32_e32 v147, v158, v220
	v_exp_f32_e32 v158, v147
	v_sub_f32_e32 v147, v176, v220
	v_exp_f32_e32 v174, v147
	v_sub_f32_e32 v147, v178, v220
	v_exp_f32_e32 v172, v147
	v_sub_f32_e32 v147, v180, v220
	v_exp_f32_e32 v176, v147
	v_sub_f32_e32 v147, v182, v220
	v_exp_f32_e32 v180, v147
	v_sub_f32_e32 v147, v183, v220
	v_exp_f32_e32 v178, v147
	v_sub_f32_e32 v147, v184, v220
	v_exp_f32_e32 v182, v147
	v_sub_f32_e32 v147, v186, v220
	v_exp_f32_e32 v186, v147
	v_sub_f32_e32 v147, v188, v220
	v_exp_f32_e32 v184, v147
	v_sub_f32_e32 v147, v189, v220
	v_exp_f32_e32 v190, v147
	v_fmamk_f32 v147, v222, 0x3e38aa3b, v36
	v_cndmask_b32_e64 v147, v200, v147, s[4:5]
	v_fmamk_f32 v149, v223, 0x3e38aa3b, v37
	v_cmp_lt_i32_e64 s[4:5], v159, v207
	v_fmamk_f32 v166, v224, 0x3e38aa3b, v38
	v_fmamk_f32 v167, v227, 0x3e38aa3b, v33
	v_cndmask_b32_e64 v149, v200, v149, s[4:5]
	v_cmp_le_i32_e64 s[4:5], v164, v207
	v_max3_f32 v159, v147, s21, v149
	v_sub_f32_e32 v191, v219, v220
	v_cndmask_b32_e64 v164, v200, v166, s[4:5]
	v_fmamk_f32 v166, v225, 0x3e38aa3b, v39
	v_cmp_le_i32_e64 s[4:5], v165, v207
	v_exp_f32_e32 v188, v191
	v_sub_f32_e32 v146, v146, v220
	v_cndmask_b32_e64 v165, v200, v166, s[4:5]
	v_fmamk_f32 v166, v226, 0x3e38aa3b, v32
	v_cndmask_b32_e32 v166, v166, v200, vcc
	v_cmp_le_i32_e32 vcc, v151, v207
	v_max3_f32 v159, v159, v164, v165
	v_pk_mul_f32 v[226:227], v[140:141], v[188:189] op_sel_hi:[1,0]
	v_cndmask_b32_e32 v167, v200, v167, vcc
	v_max3_f32 v151, v159, v166, v167
	v_fmamk_f32 v159, v228, 0x3e38aa3b, v34
	v_cmp_le_i32_e32 vcc, v177, v207
	v_fmamk_f32 v177, v229, 0x3e38aa3b, v35
	v_pk_mul_f32 v[224:225], v[138:139], v[188:189] op_sel_hi:[1,0]
	v_cndmask_b32_e32 v159, v200, v159, vcc
	v_cmp_le_i32_e32 vcc, v153, v207
	v_fmamk_f32 v153, v230, 0x3e38aa3b, v28
	v_pk_mul_f32 v[228:229], v[134:135], v[188:189] op_sel_hi:[1,0]
	v_cndmask_b32_e32 v177, v200, v177, vcc
	v_cmp_le_i32_e32 vcc, v179, v207
	v_max3_f32 v151, v151, v159, v177
	v_pk_mul_f32 v[234:235], v[132:133], v[188:189] op_sel_hi:[1,0]
	v_cndmask_b32_e32 v179, v200, v153, vcc
	v_fmamk_f32 v153, v231, 0x3e38aa3b, v29
	v_cmp_le_i32_e32 vcc, v155, v207
	v_pk_mul_f32 v[230:231], v[136:137], v[188:189] op_sel_hi:[1,0]
	v_exp_f32_e32 v146, v146
	v_cndmask_b32_e32 v183, v200, v153, vcc
	v_fmamk_f32 v153, v232, 0x3e38aa3b, v30
	v_cmp_le_i32_e32 vcc, v181, v207
	v_max3_f32 v151, v151, v179, v183
	v_cvt_pk_bf16_f32 v240, v146, v150
	v_cvt_pk_bf16_f32 v241, v148, v152
	v_cvt_pk_bf16_f32 v242, v156, v154
	v_cvt_pk_bf16_f32 v243, v158, v174
	s_nop 0
	v_cndmask_b32_e32 v181, v200, v153, vcc
	v_fmamk_f32 v153, v233, 0x3e38aa3b, v31
	v_cmp_le_i32_e32 vcc, v157, v207
	v_pk_mul_f32 v[232:233], v[130:131], v[188:189] op_sel_hi:[1,0]
	v_mfma_f32_16x16x32_bf16 v[224:227], v[92:95], v[240:243], v[224:227]
	v_cndmask_b32_e32 v191, v200, v153, vcc
	v_cmp_le_i32_e32 vcc, v185, v207
	v_max3_f32 v151, v151, v181, v191
	v_mfma_f32_16x16x32_bf16 v[228:231], v[96:99], v[240:243], v[228:231]
	v_cndmask_b32_e32 v185, v200, v104, vcc
	v_fmamk_f32 v104, v105, 0x3e38aa3b, v25
	v_cmp_le_i32_e32 vcc, v173, v207
	v_fmamk_f32 v105, v106, 0x3e38aa3b, v26
	v_mfma_f32_16x16x32_bf16 v[232:235], v[88:91], v[240:243], v[232:235]
	v_cndmask_b32_e32 v223, v200, v104, vcc
	v_cmp_le_i32_e32 vcc, v187, v207
	v_max3_f32 v104, v151, v185, v223
	s_mov_b64 s[4:5], 0
	v_cndmask_b32_e32 v194, v200, v105, vcc
	v_fmamk_f32 v105, v107, 0x3e38aa3b, v27
	v_cmp_le_i32_e32 vcc, v175, v207
	v_pk_mul_f32 v[106:107], v[144:145], v[188:189] op_sel_hi:[1,0]
	s_nop 0
	v_cndmask_b32_e32 v202, v200, v105, vcc
	v_max3_f32 v151, v104, v194, v202
	ds_bpermute_b32 v153, v204, v151
	v_pk_mul_f32 v[104:105], v[142:143], v[188:189] op_sel_hi:[1,0]
	s_waitcnt lgkmcnt(0)
; DI unsigned pk2(float lo, float hi) { unsigned r; asm volatile("v_cvt_pk_bf16_f32 %0, %1, %2" : "=v"(r) : "v"(lo), "v"(hi)); return r; }
; DI float ex2(float x) { return __builtin_amdgcn_exp2f(x); }
; DI f32x4 mmaT(bf16x8 a_m, bf16x8 b_n, f32x4 c) { return __builtin_amdgcn_mfma_f32_16x16x32_bf16(b_n, a_m, c, 0, 0, 0); }
; DI float shx(float v, int m, int lane) { return __int_as_float(__builtin_amdgcn_ds_bpermute((lane ^ m) << 2, __float_as_int(v))); }
; template <bool DIAG>
; DI void fox_tile(const bf16_t* sK, const bf16_t* sV, const float* sFk, const bf16x8 (&qf)[2][2], f32x4 (&o)[2][4], float (&mrun)[2], float (&lsum)[2], int key0, int qg0, int fr, int fq, int lane) {
;     ...
;     mx = fmaxf(mx, shx(mx, 16, lane)); mx = fmaxf(mx, shx(mx, 32, lane));
;     const float mnew = fmaxf(mrun[mi], mx), alpha = ex2(mrun[mi] - mnew);
;     mrun[mi] = mnew;
;     float ps = 0.f;
; #pragma unroll
;     for (int t = 0; t < 4; ++t)
; #pragma unroll
;       for (int j = 0; j < 4; ++j) { const float pv = ex2(s[mi][t][j] - mnew); s[mi][t][j] = pv; ps += pv; }
;     lsum[mi] = lsum[mi] * alpha + ps;
; #pragma unroll
;     for (int d = 0; d < 4; ++d) o[mi][d] *= alpha;
;   }
; #pragma unroll
;   for (int k2 = 0; k2 < 2; ++k2) {
;     bf16x8 pa[2];
; #pragma unroll
;     for (int mi = 0; mi < 2; ++mi) pa[mi] = mk8(pk2(s[mi][2 * k2][0], s[mi][2 * k2][1]), pk2(s[mi][2 * k2][2], s[mi][2 * k2][3]), pk2(s[mi][2 * k2 + 1][0], s[mi][2 * k2 + 1][1]), pk2(s[mi][2 * k2 + 1][2], s[mi][2 * k2 + 1][3]));
; #pragma unroll
;     for (int d = 0; d < 4; ++d) {
; #pragma unroll
;       for (int mi = 0; mi < 2; ++mi) o[mi][d] = mmaT(pa[mi], vf[k2][d], o[mi][d]);
;     }
	v_max_f32_e32 v153, v153, v153
	v_max_f32_e32 v151, v151, v153
	ds_bpermute_b32 v153, v169, v151
	v_mfma_f32_16x16x32_bf16 v[104:107], v[100:103], v[240:243], v[104:107]
	s_waitcnt lgkmcnt(0)
	v_max3_f32 v222, v218, v151, v153
	v_sub_f32_e32 v173, v218, v222
	v_sub_f32_e32 v149, v149, v222
	v_exp_f32_e32 v189, v173
	v_exp_f32_e32 v151, v149
	v_sub_f32_e32 v149, v164, v222
	v_sub_f32_e32 v164, v177, v222
	v_exp_f32_e32 v175, v164
	v_sub_f32_e32 v164, v179, v222
	v_exp_f32_e32 v173, v164
	v_sub_f32_e32 v164, v183, v222
	v_exp_f32_e32 v177, v164
	v_mov_b32_e32 v164, v189
	v_sub_f32_e32 v153, v165, v222
	v_sub_f32_e32 v155, v166, v222
	v_pk_mul_f32 v[238:239], v[124:125], v[164:165] op_sel_hi:[1,0]
	v_pk_mul_f32 v[236:237], v[122:123], v[164:165] op_sel_hi:[1,0]
	v_sub_f32_e32 v165, v181, v222
	v_sub_f32_e32 v147, v147, v222
	v_exp_f32_e32 v157, v155
	v_sub_f32_e32 v155, v167, v222
	v_sub_f32_e32 v159, v159, v222
	v_exp_f32_e32 v181, v165
	v_sub_f32_e32 v165, v191, v222
	v_exp_f32_e32 v147, v147
	v_exp_f32_e32 v149, v149
	v_exp_f32_e32 v153, v153
	v_exp_f32_e32 v155, v155
	v_exp_f32_e32 v159, v159
	v_cvt_pk_bf16_f32 v244, v147, v151
	v_cvt_pk_bf16_f32 v245, v149, v153
	v_cvt_pk_bf16_f32 v246, v157, v155
	v_cvt_pk_bf16_f32 v247, v159, v175
	v_exp_f32_e32 v179, v165
	v_mfma_f32_16x16x32_bf16 v[100:103], v[100:103], v[244:247], v[236:239]
	s_nop 2
	v_mul_f32_e64 v238, v120, v164
	v_mul_f32_e64 v239, v121, v164
	v_pk_mul_f32 v[236:237], v[118:119], v[164:165] op_sel_hi:[1,0]
	s_nop 1
	v_mfma_f32_16x16x32_bf16 v[236:239], v[92:95], v[244:247], v[236:239]
	v_sub_f32_e32 v92, v185, v222
	v_exp_f32_e32 v183, v92
	v_sub_f32_e32 v92, v223, v222
	v_exp_f32_e32 v187, v92
	v_pk_mul_f32 v[94:95], v[116:117], v[164:165] op_sel_hi:[1,0]
	v_pk_mul_f32 v[92:93], v[114:115], v[164:165] op_sel_hi:[1,0]
	s_nop 1
	v_mfma_f32_16x16x32_bf16 v[248:251], v[96:99], v[244:247], v[92:95]
	s_nop 2
	v_sub_f32_e32 v92, v194, v222
	v_exp_f32_e32 v185, v92
	v_sub_f32_e32 v92, v202, v222
	v_exp_f32_e32 v191, v92
	v_pk_mul_f32 v[94:95], v[112:113], v[164:165] op_sel_hi:[1,0]
	v_pk_mul_f32 v[92:93], v[110:111], v[164:165] op_sel_hi:[1,0]
	s_nop 1
	v_mfma_f32_16x16x32_bf16 v[240:243], v[88:91], v[244:247], v[92:95]
	v_cvt_pk_bf16_f32 v244, v172, v176
	v_cvt_pk_bf16_f32 v245, v180, v178
	v_cvt_pk_bf16_f32 v246, v182, v186
	v_cvt_pk_bf16_f32 v247, v184, v190
	v_cvt_pk_bf16_f32 v164, v173, v177
	v_cvt_pk_bf16_f32 v165, v181, v179
	v_cvt_pk_bf16_f32 v166, v183, v187
	v_cvt_pk_bf16_f32 v167, v185, v191
	s_nop 0
	v_mfma_f32_16x16x32_bf16 v[88:91], v[84:87], v[244:247], v[104:107]
	v_mfma_f32_16x16x32_bf16 v[92:95], v[84:87], v[164:167], v[100:103]
	v_add_f32_e64 v84, v146, 0
	v_add_f32_e64 v85, v147, 0
	v_pk_add_f32 v[96:97], v[150:151], v[84:85]
	v_mfma_f32_16x16x32_bf16 v[84:87], v[80:83], v[244:247], v[224:227]
	v_add_f32_e64 v96, v148, v96
	v_add_f32_e64 v97, v149, v97
	v_pk_add_f32 v[96:97], v[152:153], v[96:97]
	s_nop 0
	v_pk_add_f32 v[100:101], v[156:157], v[96:97]
	v_mfma_f32_16x16x32_bf16 v[96:99], v[80:83], v[164:167], v[236:239]
	v_add_f32_e64 v80, v154, v100
	v_add_f32_e64 v81, v155, v101
	v_pk_add_f32 v[80:81], v[158:159], v[80:81]
	s_nop 0
	v_pk_add_f32 v[100:101], v[174:175], v[80:81]
	v_mfma_f32_16x16x32_bf16 v[80:83], v[76:79], v[244:247], v[228:231]
	v_add_f32_e64 v100, v172, v100
	v_add_f32_e64 v101, v173, v101
	v_pk_add_f32 v[100:101], v[176:177], v[100:101]
	s_nop 0
	v_pk_add_f32 v[104:105], v[180:181], v[100:101]
	v_mfma_f32_16x16x32_bf16 v[100:103], v[76:79], v[164:167], v[248:251]
	v_add_f32_e64 v76, v178, v104
	v_add_f32_e64 v77, v179, v105
	v_pk_add_f32 v[76:77], v[182:183], v[76:77]
	s_nop 0
	v_pk_add_f32 v[104:105], v[186:187], v[76:77]
	v_mfma_f32_16x16x32_bf16 v[76:79], v[72:75], v[244:247], v[232:235]
	v_add_f32_e64 v104, v184, v104
	v_add_f32_e64 v105, v185, v105
	v_pk_add_f32 v[104:105], v[190:191], v[104:105]
	v_mfma_f32_16x16x32_bf16 v[72:75], v[72:75], v[164:167], v[240:243]
	v_fma_f32 v104, v128, v188, v104
	v_fma_f32 v105, v129, v189, v105

; DI unsigned pk2(float lo, float hi) { unsigned r; asm volatile("v_cvt_pk_bf16_f32 %0, %1, %2" : "=v"(r) : "v"(lo), "v"(hi)); return r; }
; DI float bflo(unsigned u) { return __uint_as_float(u << 16); }
; DI float bfhi(unsigned u) { return __uint_as_float(u & 0xffff0000u); }
; DI float silu_f(float x) { return x * __builtin_amdgcn_rcpf(1.0f + __expf(-x)); }
; DI float shx(float v, int m, int lane) { return __int_as_float(__builtin_amdgcn_ds_bpermute((lane ^ m) << 2, __float_as_int(v))); }
; DI void fox_unit(const Params& p, int hf, int bl, int fh, int qb, unsigned char* shm, int tid, bool dry = false) {
;     ...
;   for (int mi = 0; mi < 2; ++mi) {
;     float l = lsum[mi]; l += shx(l, 16, lane); l += shx(l, 32, lane);
;     const float inv = 1.0f / l;
;     bf16_t* gp = projb + (size_t)(qg0 + 16 * mi) * NP + C_FG + fh * 64 + 4 * fq;
; #pragma unroll
;     for (int d = 0; d < 4; ++d) {
;       const uint2 gv = *(const uint2*)(gp + 16 * d);
;       uint2 w;
;       w.x = pk2(o[mi][d][0] * inv * silu_f(bflo(gv.x)), o[mi][d][1] * inv * silu_f(bfhi(gv.x)));
;       w.y = pk2(o[mi][d][2] * inv * silu_f(bflo(gv.y)), o[mi][d][3] * inv * silu_f(bfhi(gv.y)));
;       if (!dry || inv == 1.2345e-30f) *(uint2*)(gp + 16 * d) = w;
;     }
.LBB0_620:
	ds_bpermute_b32 v0, v204, v128
	v_mov_b32_e32 v27, v161
	s_mov_b64 s[6:7], 0x3000
	s_movk_i32 s4, 0x3000
	s_waitcnt lgkmcnt(0)
	v_add_f32_e32 v0, v128, v0
	ds_bpermute_b32 v1, v169, v0
	s_waitcnt lgkmcnt(0)
	v_add_f32_e32 v0, v0, v1
	v_div_scale_f32 v1, s[0:1], v0, v0, 1.0
	v_rcp_f32_e32 v2, v1
	s_nop 0
	v_fma_f32 v3, -v1, v2, 1.0
	v_fmac_f32_e32 v2, v3, v2
	v_div_scale_f32 v3, vcc, 1.0, v0, 1.0
	v_mul_f32_e32 v4, v3, v2
	v_fma_f32 v5, -v1, v4, v3
	v_fmac_f32_e32 v4, v5, v2
	v_fma_f32 v1, -v1, v4, v3
	v_div_fmas_f32 v1, v1, v2, v4
	v_div_fixup_f32 v6, v1, v0, 1.0
	v_lshl_add_u64 v[2:3], v[126:127], 0, s[2:3]
	v_lshlrev_b64 v[0:1], 1, v[26:27]
	v_lshl_add_u64 v[4:5], v[2:3], 0, v[0:1]
	v_lshl_add_u64 v[2:3], v[4:5], 0, s[6:7]
	v_add_co_u32_e32 v4, vcc, s4, v4
	v_mul_f32_e32 v7, v142, v6
	s_nop 0
	v_addc_co_u32_e32 v5, vcc, 0, v5, vcc
	global_load_dwordx2 v[8:9], v[4:5], off
	s_waitcnt vmcnt(0)
	v_lshlrev_b32_e32 v10, 16, v8
	v_mul_f32_e32 v11, 0xbfb8aa3b, v10
	v_exp_f32_e32 v11, v11
	v_and_b32_e32 v8, 0xffff0000, v8
	v_add_f32_e32 v11, 1.0, v11
	v_rcp_f32_e32 v11, v11
	s_nop 0
	v_mul_f32_e32 v10, v11, v10
	v_mul_f32_e32 v11, 0xbfb8aa3b, v8
	v_exp_f32_e32 v11, v11
	v_mul_f32_e32 v7, v7, v10
	v_mul_f32_e32 v10, v143, v6
	v_add_f32_e32 v11, 1.0, v11
	v_rcp_f32_e32 v11, v11
	s_nop 0
	v_mul_f32_e32 v8, v11, v8
	v_mul_f32_e32 v8, v10, v8
	v_lshlrev_b32_e32 v10, 16, v9
	v_mul_f32_e32 v11, 0xbfb8aa3b, v10
	v_exp_f32_e32 v11, v11
	v_and_b32_e32 v9, 0xffff0000, v9
	v_cvt_pk_bf16_f32 v8, v7, v8
	v_mul_f32_e32 v7, v144, v6
	v_add_f32_e32 v11, 1.0, v11
	v_rcp_f32_e32 v11, v11
	s_nop 0
	v_mul_f32_e32 v10, v11, v10
	v_mul_f32_e32 v11, 0xbfb8aa3b, v9
	v_exp_f32_e32 v11, v11
	v_mul_f32_e32 v7, v7, v10
	v_mul_f32_e32 v10, v145, v6
	v_add_f32_e32 v11, 1.0, v11
	v_rcp_f32_e32 v11, v11
	s_nop 0
	v_mul_f32_e32 v9, v11, v9
	v_mul_f32_e32 v9, v10, v9
	v_cvt_pk_bf16_f32 v9, v7, v9
	global_store_dwordx2 v[4:5], v[8:9], off
	global_load_dwordx2 v[4:5], v[2:3], off offset:32
	v_mul_f32_e32 v7, v138, v6
	s_waitcnt vmcnt(0)
	v_lshlrev_b32_e32 v8, 16, v4
	v_mul_f32_e32 v9, 0xbfb8aa3b, v8
	v_exp_f32_e32 v9, v9
	v_and_b32_e32 v4, 0xffff0000, v4
	v_add_f32_e32 v9, 1.0, v9
	v_rcp_f32_e32 v9, v9
	s_nop 0
	v_mul_f32_e32 v8, v9, v8
	v_mul_f32_e32 v9, 0xbfb8aa3b, v4
	v_exp_f32_e32 v9, v9
	v_mul_f32_e32 v7, v7, v8
	v_mul_f32_e32 v8, v139, v6
	v_add_f32_e32 v9, 1.0, v9
	v_rcp_f32_e32 v9, v9
	s_nop 0
	v_mul_f32_e32 v4, v9, v4
	v_mul_f32_e32 v4, v8, v4
	v_lshlrev_b32_e32 v8, 16, v5
	v_mul_f32_e32 v9, 0xbfb8aa3b, v8
	v_exp_f32_e32 v9, v9
	v_and_b32_e32 v5, 0xffff0000, v5
	v_cvt_pk_bf16_f32 v4, v7, v4
	v_mul_f32_e32 v7, v140, v6
	v_add_f32_e32 v9, 1.0, v9
	v_rcp_f32_e32 v9, v9
	s_nop 0
	v_mul_f32_e32 v8, v9, v8
	v_mul_f32_e32 v9, 0xbfb8aa3b, v5
	v_exp_f32_e32 v9, v9
	v_mul_f32_e32 v7, v7, v8
	v_mul_f32_e32 v8, v141, v6
	v_add_f32_e32 v9, 1.0, v9
	v_rcp_f32_e32 v9, v9
	s_nop 0
	v_mul_f32_e32 v5, v9, v5
	v_mul_f32_e32 v5, v8, v5
	v_cvt_pk_bf16_f32 v5, v7, v5
	global_store_dwordx2 v[2:3], v[4:5], off offset:32
	global_load_dwordx2 v[4:5], v[2:3], off offset:64
	v_mul_f32_e32 v7, v134, v6
	s_waitcnt vmcnt(0)
	v_lshlrev_b32_e32 v8, 16, v4
	v_mul_f32_e32 v9, 0xbfb8aa3b, v8
	v_exp_f32_e32 v9, v9
	v_and_b32_e32 v4, 0xffff0000, v4
	v_add_f32_e32 v9, 1.0, v9
	v_rcp_f32_e32 v9, v9
	s_nop 0
	v_mul_f32_e32 v8, v9, v8
	v_mul_f32_e32 v9, 0xbfb8aa3b, v4
	v_exp_f32_e32 v9, v9
	v_mul_f32_e32 v7, v7, v8
	v_mul_f32_e32 v8, v135, v6
	v_add_f32_e32 v9, 1.0, v9
	v_rcp_f32_e32 v9, v9
	s_nop 0
	v_mul_f32_e32 v4, v9, v4
	v_mul_f32_e32 v4, v8, v4
	v_lshlrev_b32_e32 v8, 16, v5
	v_mul_f32_e32 v9, 0xbfb8aa3b, v8
	v_exp_f32_e32 v9, v9
	v_and_b32_e32 v5, 0xffff0000, v5
	v_cvt_pk_bf16_f32 v4, v7, v4
	v_mul_f32_e32 v7, v136, v6
	v_add_f32_e32 v9, 1.0, v9
	v_rcp_f32_e32 v9, v9
	s_nop 0
	v_mul_f32_e32 v8, v9, v8
	v_mul_f32_e32 v9, 0xbfb8aa3b, v5
	v_exp_f32_e32 v9, v9
	v_mul_f32_e32 v7, v7, v8
	v_mul_f32_e32 v8, v137, v6
	v_add_f32_e32 v9, 1.0, v9
	v_rcp_f32_e32 v9, v9
	s_nop 0
	v_mul_f32_e32 v5, v9, v5
	v_mul_f32_e32 v5, v8, v5
	v_cvt_pk_bf16_f32 v5, v7, v5
	global_store_dwordx2 v[2:3], v[4:5], off offset:64
	global_load_dwordx2 v[4:5], v[2:3], off offset:96
	v_mul_f32_e32 v7, v130, v6
	s_waitcnt vmcnt(0)
	v_lshlrev_b32_e32 v8, 16, v4
	v_mul_f32_e32 v9, 0xbfb8aa3b, v8
	v_exp_f32_e32 v9, v9
	v_and_b32_e32 v4, 0xffff0000, v4
	v_add_f32_e32 v9, 1.0, v9
	v_rcp_f32_e32 v9, v9
	s_nop 0
	v_mul_f32_e32 v8, v9, v8
	v_mul_f32_e32 v9, 0xbfb8aa3b, v4
	v_exp_f32_e32 v9, v9
	v_mul_f32_e32 v7, v7, v8
	v_mul_f32_e32 v8, v131, v6
	v_add_f32_e32 v9, 1.0, v9
	v_rcp_f32_e32 v9, v9
	s_nop 0
	v_mul_f32_e32 v4, v9, v4
	v_mul_f32_e32 v4, v8, v4
	v_lshlrev_b32_e32 v8, 16, v5
	v_mul_f32_e32 v9, 0xbfb8aa3b, v8
	v_exp_f32_e32 v9, v9
	v_cvt_pk_bf16_f32 v4, v7, v4
	v_mul_f32_e32 v7, v132, v6
	v_and_b32_e32 v5, 0xffff0000, v5
	v_add_f32_e32 v9, 1.0, v9
	v_rcp_f32_e32 v9, v9
	v_mul_f32_e32 v6, v133, v6
	v_mul_f32_e32 v8, v9, v8
	v_mul_f32_e32 v7, v7, v8
	v_mul_f32_e32 v8, 0xbfb8aa3b, v5
	v_exp_f32_e32 v8, v8
	s_nop 0
	v_add_f32_e32 v8, 1.0, v8
	v_rcp_f32_e32 v8, v8
	s_nop 0
	v_mul_f32_e32 v5, v8, v5
	v_mul_f32_e32 v5, v6, v5
	v_cvt_pk_bf16_f32 v5, v7, v5
	global_store_dwordx2 v[2:3], v[4:5], off offset:96
	ds_bpermute_b32 v2, v204, v129
	s_waitcnt lgkmcnt(0)
; DI unsigned pk2(float lo, float hi) { unsigned r; asm volatile("v_cvt_pk_bf16_f32 %0, %1, %2" : "=v"(r) : "v"(lo), "v"(hi)); return r; }
; DI float bflo(unsigned u) { return __uint_as_float(u << 16); }
; DI float bfhi(unsigned u) { return __uint_as_float(u & 0xffff0000u); }
; DI float silu_f(float x) { return x * __builtin_amdgcn_rcpf(1.0f + __expf(-x)); }
; DI float shx(float v, int m, int lane) { return __int_as_float(__builtin_amdgcn_ds_bpermute((lane ^ m) << 2, __float_as_int(v))); }
; DI void fox_unit(const Params& p, int hf, int bl, int fh, int qb, unsigned char* shm, int tid, bool dry = false) {
;     ...
;   for (int mi = 0; mi < 2; ++mi) {
;     float l = lsum[mi]; l += shx(l, 16, lane); l += shx(l, 32, lane);
;     const float inv = 1.0f / l;
;     bf16_t* gp = projb + (size_t)(qg0 + 16 * mi) * NP + C_FG + fh * 64 + 4 * fq;
; #pragma unroll
;     for (int d = 0; d < 4; ++d) {
;       const uint2 gv = *(const uint2*)(gp + 16 * d);
;       uint2 w;
;       w.x = pk2(o[mi][d][0] * inv * silu_f(bflo(gv.x)), o[mi][d][1] * inv * silu_f(bfhi(gv.x)));
;       w.y = pk2(o[mi][d][2] * inv * silu_f(bflo(gv.y)), o[mi][d][3] * inv * silu_f(bfhi(gv.y)));
;       if (!dry || inv == 1.2345e-30f) *(uint2*)(gp + 16 * d) = w;
;     }
	v_add_f32_e32 v2, v129, v2
	ds_bpermute_b32 v3, v169, v2
	s_waitcnt lgkmcnt(0)
	v_add_f32_e32 v2, v2, v3
	v_div_scale_f32 v3, s[0:1], v2, v2, 1.0
	v_rcp_f32_e32 v4, v3
	s_nop 0
	v_fma_f32 v5, -v3, v4, 1.0
	v_fmac_f32_e32 v4, v5, v4
	v_div_scale_f32 v5, vcc, 1.0, v2, 1.0
	v_mul_f32_e32 v6, v5, v4
	v_fma_f32 v7, -v3, v6, v5
	v_fmac_f32_e32 v6, v7, v4
	v_fma_f32 v3, -v3, v6, v5
	v_div_fmas_f32 v3, v3, v4, v6
	v_div_fixup_f32 v4, v3, v2, 1.0
	v_lshl_add_u64 v[2:3], v[108:109], 0, s[2:3]
	v_lshl_add_u64 v[2:3], v[2:3], 0, v[0:1]
	v_lshl_add_u64 v[0:1], v[2:3], 0, s[6:7]
	v_add_co_u32_e32 v2, vcc, s4, v2
	v_mul_f32_e32 v5, v122, v4
	s_nop 0
	v_addc_co_u32_e32 v3, vcc, 0, v3, vcc
	global_load_dwordx2 v[6:7], v[2:3], off
	v_readlane_b32 s6, v254, 55
	v_readlane_b32 s7, v254, 56
	s_waitcnt vmcnt(0)
	v_lshlrev_b32_e32 v8, 16, v6
	v_mul_f32_e32 v9, 0xbfb8aa3b, v8
	v_exp_f32_e32 v9, v9
	v_and_b32_e32 v6, 0xffff0000, v6
	v_add_f32_e32 v9, 1.0, v9
	v_rcp_f32_e32 v9, v9
	s_nop 0
	v_mul_f32_e32 v8, v9, v8
	v_mul_f32_e32 v9, 0xbfb8aa3b, v6
	v_exp_f32_e32 v9, v9
	v_mul_f32_e32 v5, v5, v8
	v_mul_f32_e32 v8, v123, v4
	v_add_f32_e32 v9, 1.0, v9
	v_rcp_f32_e32 v9, v9
	s_nop 0
	v_mul_f32_e32 v6, v9, v6
	v_mul_f32_e32 v6, v8, v6
	v_lshlrev_b32_e32 v8, 16, v7
	v_mul_f32_e32 v9, 0xbfb8aa3b, v8
	v_exp_f32_e32 v9, v9
	v_and_b32_e32 v7, 0xffff0000, v7
	v_cvt_pk_bf16_f32 v6, v5, v6
	v_mul_f32_e32 v5, v124, v4
	v_add_f32_e32 v9, 1.0, v9
	v_rcp_f32_e32 v9, v9
	s_nop 0
	v_mul_f32_e32 v8, v9, v8
	v_mul_f32_e32 v9, 0xbfb8aa3b, v7
	v_exp_f32_e32 v9, v9
	v_mul_f32_e32 v5, v5, v8
	v_mul_f32_e32 v8, v125, v4
	v_add_f32_e32 v9, 1.0, v9
	v_rcp_f32_e32 v9, v9
	s_nop 0
	v_mul_f32_e32 v7, v9, v7
	v_mul_f32_e32 v7, v8, v7
	v_cvt_pk_bf16_f32 v7, v5, v7
	global_store_dwordx2 v[2:3], v[6:7], off
	global_load_dwordx2 v[2:3], v[0:1], off offset:32
	v_mul_f32_e32 v5, v118, v4
	s_waitcnt vmcnt(0)
	v_lshlrev_b32_e32 v6, 16, v2
	v_mul_f32_e32 v7, 0xbfb8aa3b, v6
	v_exp_f32_e32 v7, v7
	v_and_b32_e32 v2, 0xffff0000, v2
	v_add_f32_e32 v7, 1.0, v7
	v_rcp_f32_e32 v7, v7
	s_nop 0
	v_mul_f32_e32 v6, v7, v6
	v_mul_f32_e32 v7, 0xbfb8aa3b, v2
	v_exp_f32_e32 v7, v7
	v_mul_f32_e32 v5, v5, v6
	v_mul_f32_e32 v6, v119, v4
	v_add_f32_e32 v7, 1.0, v7
	v_rcp_f32_e32 v7, v7
	s_nop 0
	v_mul_f32_e32 v2, v7, v2
	v_mul_f32_e32 v2, v6, v2
	v_lshlrev_b32_e32 v6, 16, v3
	v_mul_f32_e32 v7, 0xbfb8aa3b, v6
	v_exp_f32_e32 v7, v7
	v_and_b32_e32 v3, 0xffff0000, v3
	v_cvt_pk_bf16_f32 v2, v5, v2
	v_mul_f32_e32 v5, v120, v4
	v_add_f32_e32 v7, 1.0, v7
	v_rcp_f32_e32 v7, v7
	s_nop 0
	v_mul_f32_e32 v6, v7, v6
	v_mul_f32_e32 v7, 0xbfb8aa3b, v3
	v_exp_f32_e32 v7, v7
	v_mul_f32_e32 v5, v5, v6
	v_mul_f32_e32 v6, v121, v4
	v_add_f32_e32 v7, 1.0, v7
	v_rcp_f32_e32 v7, v7
	s_nop 0
	v_mul_f32_e32 v3, v7, v3
	v_mul_f32_e32 v3, v6, v3
	v_cvt_pk_bf16_f32 v3, v5, v3
	global_store_dwordx2 v[0:1], v[2:3], off offset:32
	global_load_dwordx2 v[2:3], v[0:1], off offset:64
	v_mul_f32_e32 v5, v114, v4
	s_waitcnt vmcnt(0)
	v_lshlrev_b32_e32 v6, 16, v2
	v_mul_f32_e32 v7, 0xbfb8aa3b, v6
	v_exp_f32_e32 v7, v7
	v_and_b32_e32 v2, 0xffff0000, v2
	v_add_f32_e32 v7, 1.0, v7
	v_rcp_f32_e32 v7, v7
	s_nop 0
	v_mul_f32_e32 v6, v7, v6
	v_mul_f32_e32 v7, 0xbfb8aa3b, v2
	v_exp_f32_e32 v7, v7
	v_mul_f32_e32 v5, v5, v6
	v_mul_f32_e32 v6, v115, v4
	v_add_f32_e32 v7, 1.0, v7
	v_rcp_f32_e32 v7, v7
	s_nop 0
	v_mul_f32_e32 v2, v7, v2
	v_mul_f32_e32 v2, v6, v2
	v_lshlrev_b32_e32 v6, 16, v3
	v_mul_f32_e32 v7, 0xbfb8aa3b, v6
	v_exp_f32_e32 v7, v7
	v_and_b32_e32 v3, 0xffff0000, v3
	v_cvt_pk_bf16_f32 v2, v5, v2
	v_mul_f32_e32 v5, v116, v4
	v_add_f32_e32 v7, 1.0, v7
	v_rcp_f32_e32 v7, v7
	s_nop 0
	v_mul_f32_e32 v6, v7, v6
	v_mul_f32_e32 v7, 0xbfb8aa3b, v3
	v_exp_f32_e32 v7, v7
	v_mul_f32_e32 v5, v5, v6
	v_mul_f32_e32 v6, v117, v4
	v_add_f32_e32 v7, 1.0, v7
	v_rcp_f32_e32 v7, v7
	s_nop 0
	v_mul_f32_e32 v3, v7, v3
	v_mul_f32_e32 v3, v6, v3
	v_cvt_pk_bf16_f32 v3, v5, v3
	global_store_dwordx2 v[0:1], v[2:3], off offset:64
	global_load_dwordx2 v[2:3], v[0:1], off offset:96
	v_mul_f32_e32 v5, v110, v4
	s_waitcnt vmcnt(0)
	v_lshlrev_b32_e32 v6, 16, v2
	v_mul_f32_e32 v7, 0xbfb8aa3b, v6
	v_exp_f32_e32 v7, v7
	v_and_b32_e32 v2, 0xffff0000, v2
	v_add_f32_e32 v7, 1.0, v7
	v_rcp_f32_e32 v7, v7
	s_nop 0
	v_mul_f32_e32 v6, v7, v6
	v_mul_f32_e32 v7, 0xbfb8aa3b, v2
	v_exp_f32_e32 v7, v7
	v_mul_f32_e32 v5, v5, v6
	v_mul_f32_e32 v6, v111, v4
	v_add_f32_e32 v7, 1.0, v7
	v_rcp_f32_e32 v7, v7
	s_nop 0
	v_mul_f32_e32 v2, v7, v2
	v_mul_f32_e32 v2, v6, v2
	v_lshlrev_b32_e32 v6, 16, v3
	v_mul_f32_e32 v7, 0xbfb8aa3b, v6
	v_exp_f32_e32 v7, v7
	v_cvt_pk_bf16_f32 v2, v5, v2
	v_mul_f32_e32 v5, v112, v4
	v_and_b32_e32 v3, 0xffff0000, v3
	v_add_f32_e32 v7, 1.0, v7
	v_rcp_f32_e32 v7, v7
	v_mul_f32_e32 v4, v113, v4
	v_mul_f32_e32 v6, v7, v6
	v_mul_f32_e32 v5, v5, v6
	v_mul_f32_e32 v6, 0xbfb8aa3b, v3
	v_exp_f32_e32 v6, v6
	s_nop 0
	v_add_f32_e32 v6, 1.0, v6
	v_rcp_f32_e32 v6, v6
	s_nop 0
	v_mul_f32_e32 v3, v6, v3
	v_mul_f32_e32 v3, v4, v3
	v_cvt_pk_bf16_f32 v3, v5, v3
	global_store_dwordx2 v[0:1], v[2:3], off offset:96
	v_mov_b32_e32 v198, 0x7f800000
	v_mov_b32_e32 v199, 0x7fc00000

; DI unsigned pk2(float lo, float hi) { unsigned r; asm volatile("v_cvt_pk_bf16_f32 %0, %1, %2" : "=v"(r) : "v"(lo), "v"(hi)); return r; }
; DI float bflo(unsigned u) { return __uint_as_float(u << 16); }
; DI float bfhi(unsigned u) { return __uint_as_float(u & 0xffff0000u); }
; DI float silu_f(float x) { return x * __builtin_amdgcn_rcpf(1.0f + __expf(-x)); }
; DI float shx(float v, int m, int lane) { return __int_as_float(__builtin_amdgcn_ds_bpermute((lane ^ m) << 2, __float_as_int(v))); }
; DI void fox_unit(const Params& p, int hf, int bl, int fh, int qb, unsigned char* shm, int tid, bool dry = false) {
;     ...
;   for (int mi = 0; mi < 2; ++mi) {
;     float l = lsum[mi]; l += shx(l, 16, lane); l += shx(l, 32, lane);
;     const float inv = 1.0f / l;
;     bf16_t* gp = projb + (size_t)(qg0 + 16 * mi) * NP + C_FG + fh * 64 + 4 * fq;
; #pragma unroll
;     for (int d = 0; d < 4; ++d) {
;       const uint2 gv = *(const uint2*)(gp + 16 * d);
;       uint2 w;
;       w.x = pk2(o[mi][d][0] * inv * silu_f(bflo(gv.x)), o[mi][d][1] * inv * silu_f(bfhi(gv.x)));
;       w.y = pk2(o[mi][d][2] * inv * silu_f(bflo(gv.y)), o[mi][d][3] * inv * silu_f(bfhi(gv.y)));
;       if (!dry || inv == 1.2345e-30f) *(uint2*)(gp + 16 * d) = w;
;     }
.LBB0_635:
	ds_bpermute_b32 v0, v204, v128
	v_mov_b32_e32 v27, v161
	s_mov_b64 s[6:7], 0x3000
	s_movk_i32 s4, 0x3000
	s_waitcnt lgkmcnt(0)
	v_add_f32_e32 v0, v128, v0
	ds_bpermute_b32 v1, v169, v0
	s_waitcnt lgkmcnt(0)
	v_add_f32_e32 v0, v0, v1
	v_div_scale_f32 v1, s[0:1], v0, v0, 1.0
	v_rcp_f32_e32 v2, v1
	s_nop 0
	v_fma_f32 v3, -v1, v2, 1.0
	v_fmac_f32_e32 v2, v3, v2
	v_div_scale_f32 v3, vcc, 1.0, v0, 1.0
	v_mul_f32_e32 v4, v3, v2
	v_fma_f32 v5, -v1, v4, v3
	v_fmac_f32_e32 v4, v5, v2
	v_fma_f32 v1, -v1, v4, v3
	v_div_fmas_f32 v1, v1, v2, v4
	v_div_fixup_f32 v6, v1, v0, 1.0
	v_lshl_add_u64 v[2:3], v[126:127], 0, s[2:3]
	v_lshlrev_b64 v[0:1], 1, v[26:27]
	v_lshl_add_u64 v[4:5], v[2:3], 0, v[0:1]
	v_lshl_add_u64 v[2:3], v[4:5], 0, s[6:7]
	v_add_co_u32_e32 v4, vcc, s4, v4
	v_mul_f32_e32 v7, v142, v6
	s_nop 0
	v_addc_co_u32_e32 v5, vcc, 0, v5, vcc
	global_load_dwordx2 v[8:9], v[4:5], off
	s_waitcnt vmcnt(0)
	v_lshlrev_b32_e32 v10, 16, v8
	v_mul_f32_e32 v11, 0xbfb8aa3b, v10
	v_exp_f32_e32 v11, v11
	v_and_b32_e32 v8, 0xffff0000, v8
	v_add_f32_e32 v11, 1.0, v11
	v_rcp_f32_e32 v11, v11
	s_nop 0
	v_mul_f32_e32 v10, v11, v10
	v_mul_f32_e32 v11, 0xbfb8aa3b, v8
	v_exp_f32_e32 v11, v11
	v_mul_f32_e32 v7, v7, v10
	v_mul_f32_e32 v10, v143, v6
	v_add_f32_e32 v11, 1.0, v11
	v_rcp_f32_e32 v11, v11
	s_nop 0
	v_mul_f32_e32 v8, v11, v8
	v_mul_f32_e32 v8, v10, v8
	v_lshlrev_b32_e32 v10, 16, v9
	v_mul_f32_e32 v11, 0xbfb8aa3b, v10
	v_exp_f32_e32 v11, v11
	v_and_b32_e32 v9, 0xffff0000, v9
	v_cvt_pk_bf16_f32 v8, v7, v8
	v_mul_f32_e32 v7, v144, v6
	v_add_f32_e32 v11, 1.0, v11
	v_rcp_f32_e32 v11, v11
	s_nop 0
	v_mul_f32_e32 v10, v11, v10
	v_mul_f32_e32 v11, 0xbfb8aa3b, v9
	v_exp_f32_e32 v11, v11
	v_mul_f32_e32 v7, v7, v10
	v_mul_f32_e32 v10, v145, v6
	v_add_f32_e32 v11, 1.0, v11
	v_rcp_f32_e32 v11, v11
	s_nop 0
	v_mul_f32_e32 v9, v11, v9
	v_mul_f32_e32 v9, v10, v9
	v_cvt_pk_bf16_f32 v9, v7, v9
	global_store_dwordx2 v[4:5], v[8:9], off
	global_load_dwordx2 v[4:5], v[2:3], off offset:32
	v_mul_f32_e32 v7, v138, v6
	s_waitcnt vmcnt(0)
	v_lshlrev_b32_e32 v8, 16, v4
	v_mul_f32_e32 v9, 0xbfb8aa3b, v8
	v_exp_f32_e32 v9, v9
	v_and_b32_e32 v4, 0xffff0000, v4
	v_add_f32_e32 v9, 1.0, v9
	v_rcp_f32_e32 v9, v9
	s_nop 0
	v_mul_f32_e32 v8, v9, v8
	v_mul_f32_e32 v9, 0xbfb8aa3b, v4
	v_exp_f32_e32 v9, v9
	v_mul_f32_e32 v7, v7, v8
	v_mul_f32_e32 v8, v139, v6
	v_add_f32_e32 v9, 1.0, v9
	v_rcp_f32_e32 v9, v9
	s_nop 0
	v_mul_f32_e32 v4, v9, v4
	v_mul_f32_e32 v4, v8, v4
	v_lshlrev_b32_e32 v8, 16, v5
	v_mul_f32_e32 v9, 0xbfb8aa3b, v8
	v_exp_f32_e32 v9, v9
	v_and_b32_e32 v5, 0xffff0000, v5
	v_cvt_pk_bf16_f32 v4, v7, v4
	v_mul_f32_e32 v7, v140, v6
	v_add_f32_e32 v9, 1.0, v9
	v_rcp_f32_e32 v9, v9
	s_nop 0
	v_mul_f32_e32 v8, v9, v8
	v_mul_f32_e32 v9, 0xbfb8aa3b, v5
	v_exp_f32_e32 v9, v9
	v_mul_f32_e32 v7, v7, v8
	v_mul_f32_e32 v8, v141, v6
	v_add_f32_e32 v9, 1.0, v9
	v_rcp_f32_e32 v9, v9
	s_nop 0
	v_mul_f32_e32 v5, v9, v5
	v_mul_f32_e32 v5, v8, v5
	v_cvt_pk_bf16_f32 v5, v7, v5
	global_store_dwordx2 v[2:3], v[4:5], off offset:32
	global_load_dwordx2 v[4:5], v[2:3], off offset:64
	v_mul_f32_e32 v7, v134, v6
	s_waitcnt vmcnt(0)
	v_lshlrev_b32_e32 v8, 16, v4
	v_mul_f32_e32 v9, 0xbfb8aa3b, v8
	v_exp_f32_e32 v9, v9
	v_and_b32_e32 v4, 0xffff0000, v4
	v_add_f32_e32 v9, 1.0, v9
	v_rcp_f32_e32 v9, v9
	s_nop 0
	v_mul_f32_e32 v8, v9, v8
	v_mul_f32_e32 v9, 0xbfb8aa3b, v4
	v_exp_f32_e32 v9, v9
	v_mul_f32_e32 v7, v7, v8
	v_mul_f32_e32 v8, v135, v6
	v_add_f32_e32 v9, 1.0, v9
	v_rcp_f32_e32 v9, v9
	s_nop 0
	v_mul_f32_e32 v4, v9, v4
	v_mul_f32_e32 v4, v8, v4
	v_lshlrev_b32_e32 v8, 16, v5
	v_mul_f32_e32 v9, 0xbfb8aa3b, v8
	v_exp_f32_e32 v9, v9
	v_and_b32_e32 v5, 0xffff0000, v5
	v_cvt_pk_bf16_f32 v4, v7, v4
	v_mul_f32_e32 v7, v136, v6
	v_add_f32_e32 v9, 1.0, v9
	v_rcp_f32_e32 v9, v9
	s_nop 0
	v_mul_f32_e32 v8, v9, v8
	v_mul_f32_e32 v9, 0xbfb8aa3b, v5
	v_exp_f32_e32 v9, v9
	v_mul_f32_e32 v7, v7, v8
	v_mul_f32_e32 v8, v137, v6
	v_add_f32_e32 v9, 1.0, v9
	v_rcp_f32_e32 v9, v9
	s_nop 0
	v_mul_f32_e32 v5, v9, v5
	v_mul_f32_e32 v5, v8, v5
	v_cvt_pk_bf16_f32 v5, v7, v5
	global_store_dwordx2 v[2:3], v[4:5], off offset:64
	global_load_dwordx2 v[4:5], v[2:3], off offset:96
	v_mul_f32_e32 v7, v130, v6
	s_waitcnt vmcnt(0)
	v_lshlrev_b32_e32 v8, 16, v4
	v_mul_f32_e32 v9, 0xbfb8aa3b, v8
	v_exp_f32_e32 v9, v9
	v_and_b32_e32 v4, 0xffff0000, v4
	v_add_f32_e32 v9, 1.0, v9
	v_rcp_f32_e32 v9, v9
	s_nop 0
	v_mul_f32_e32 v8, v9, v8
	v_mul_f32_e32 v9, 0xbfb8aa3b, v4
	v_exp_f32_e32 v9, v9
	v_mul_f32_e32 v7, v7, v8
	v_mul_f32_e32 v8, v131, v6
	v_add_f32_e32 v9, 1.0, v9
	v_rcp_f32_e32 v9, v9
	s_nop 0
	v_mul_f32_e32 v4, v9, v4
	v_mul_f32_e32 v4, v8, v4
	v_lshlrev_b32_e32 v8, 16, v5
	v_mul_f32_e32 v9, 0xbfb8aa3b, v8
	v_exp_f32_e32 v9, v9
	v_cvt_pk_bf16_f32 v4, v7, v4
	v_mul_f32_e32 v7, v132, v6
	v_and_b32_e32 v5, 0xffff0000, v5
	v_add_f32_e32 v9, 1.0, v9
	v_rcp_f32_e32 v9, v9
	v_mul_f32_e32 v6, v133, v6
	v_mul_f32_e32 v8, v9, v8
	v_mul_f32_e32 v7, v7, v8
	v_mul_f32_e32 v8, 0xbfb8aa3b, v5
	v_exp_f32_e32 v8, v8
	s_nop 0
	v_add_f32_e32 v8, 1.0, v8
	v_rcp_f32_e32 v8, v8
	s_nop 0
	v_mul_f32_e32 v5, v8, v5
	v_mul_f32_e32 v5, v6, v5
	v_cvt_pk_bf16_f32 v5, v7, v5
	global_store_dwordx2 v[2:3], v[4:5], off offset:96
	ds_bpermute_b32 v2, v204, v129
	s_waitcnt lgkmcnt(0)
; DI unsigned pk2(float lo, float hi) { unsigned r; asm volatile("v_cvt_pk_bf16_f32 %0, %1, %2" : "=v"(r) : "v"(lo), "v"(hi)); return r; }
; DI float bflo(unsigned u) { return __uint_as_float(u << 16); }
; DI float bfhi(unsigned u) { return __uint_as_float(u & 0xffff0000u); }
; DI float silu_f(float x) { return x * __builtin_amdgcn_rcpf(1.0f + __expf(-x)); }
; DI float shx(float v, int m, int lane) { return __int_as_float(__builtin_amdgcn_ds_bpermute((lane ^ m) << 2, __float_as_int(v))); }
; DI void fox_unit(const Params& p, int hf, int bl, int fh, int qb, unsigned char* shm, int tid, bool dry = false) {
;     ...
;   for (int mi = 0; mi < 2; ++mi) {
;     float l = lsum[mi]; l += shx(l, 16, lane); l += shx(l, 32, lane);
;     const float inv = 1.0f / l;
;     bf16_t* gp = projb + (size_t)(qg0 + 16 * mi) * NP + C_FG + fh * 64 + 4 * fq;
; #pragma unroll
;     for (int d = 0; d < 4; ++d) {
;       const uint2 gv = *(const uint2*)(gp + 16 * d);
;       uint2 w;
;       w.x = pk2(o[mi][d][0] * inv * silu_f(bflo(gv.x)), o[mi][d][1] * inv * silu_f(bfhi(gv.x)));
;       w.y = pk2(o[mi][d][2] * inv * silu_f(bflo(gv.y)), o[mi][d][3] * inv * silu_f(bfhi(gv.y)));
;       if (!dry || inv == 1.2345e-30f) *(uint2*)(gp + 16 * d) = w;
;     }
	v_add_f32_e32 v2, v129, v2
	ds_bpermute_b32 v3, v169, v2
	s_waitcnt lgkmcnt(0)
	v_add_f32_e32 v2, v2, v3
	v_div_scale_f32 v3, s[0:1], v2, v2, 1.0
	v_rcp_f32_e32 v4, v3
	s_nop 0
	v_fma_f32 v5, -v3, v4, 1.0
	v_fmac_f32_e32 v4, v5, v4
	v_div_scale_f32 v5, vcc, 1.0, v2, 1.0
	v_mul_f32_e32 v6, v5, v4
	v_fma_f32 v7, -v3, v6, v5
	v_fmac_f32_e32 v6, v7, v4
	v_fma_f32 v3, -v3, v6, v5
	v_div_fmas_f32 v3, v3, v4, v6
	v_div_fixup_f32 v4, v3, v2, 1.0
	v_lshl_add_u64 v[2:3], v[108:109], 0, s[2:3]
	v_lshl_add_u64 v[2:3], v[2:3], 0, v[0:1]
	v_lshl_add_u64 v[0:1], v[2:3], 0, s[6:7]
	v_add_co_u32_e32 v2, vcc, s4, v2
	v_mul_f32_e32 v5, v122, v4
	s_nop 0
	v_addc_co_u32_e32 v3, vcc, 0, v3, vcc
	global_load_dwordx2 v[6:7], v[2:3], off
	s_waitcnt vmcnt(0)
	v_lshlrev_b32_e32 v8, 16, v6
	v_mul_f32_e32 v9, 0xbfb8aa3b, v8
	v_exp_f32_e32 v9, v9
	v_and_b32_e32 v6, 0xffff0000, v6
	v_add_f32_e32 v9, 1.0, v9
	v_rcp_f32_e32 v9, v9
	s_nop 0
	v_mul_f32_e32 v8, v9, v8
	v_mul_f32_e32 v9, 0xbfb8aa3b, v6
	v_exp_f32_e32 v9, v9
	v_mul_f32_e32 v5, v5, v8
	v_mul_f32_e32 v8, v123, v4
	v_add_f32_e32 v9, 1.0, v9
	v_rcp_f32_e32 v9, v9
	s_nop 0
	v_mul_f32_e32 v6, v9, v6
	v_mul_f32_e32 v6, v8, v6
	v_lshlrev_b32_e32 v8, 16, v7
	v_mul_f32_e32 v9, 0xbfb8aa3b, v8
	v_exp_f32_e32 v9, v9
	v_and_b32_e32 v7, 0xffff0000, v7
	v_cvt_pk_bf16_f32 v6, v5, v6
	v_mul_f32_e32 v5, v124, v4
	v_add_f32_e32 v9, 1.0, v9
	v_rcp_f32_e32 v9, v9
	s_nop 0
	v_mul_f32_e32 v8, v9, v8
	v_mul_f32_e32 v9, 0xbfb8aa3b, v7
	v_exp_f32_e32 v9, v9
	v_mul_f32_e32 v5, v5, v8
	v_mul_f32_e32 v8, v125, v4
	v_add_f32_e32 v9, 1.0, v9
	v_rcp_f32_e32 v9, v9
	s_nop 0
	v_mul_f32_e32 v7, v9, v7
	v_mul_f32_e32 v7, v8, v7
	v_cvt_pk_bf16_f32 v7, v5, v7
	global_store_dwordx2 v[2:3], v[6:7], off
	global_load_dwordx2 v[2:3], v[0:1], off offset:32
	v_mul_f32_e32 v5, v118, v4
	s_waitcnt vmcnt(0)
	v_lshlrev_b32_e32 v6, 16, v2
	v_mul_f32_e32 v7, 0xbfb8aa3b, v6
	v_exp_f32_e32 v7, v7
	v_and_b32_e32 v2, 0xffff0000, v2
	v_add_f32_e32 v7, 1.0, v7
	v_rcp_f32_e32 v7, v7
	s_nop 0
	v_mul_f32_e32 v6, v7, v6
	v_mul_f32_e32 v7, 0xbfb8aa3b, v2
	v_exp_f32_e32 v7, v7
	v_mul_f32_e32 v5, v5, v6
	v_mul_f32_e32 v6, v119, v4
	v_add_f32_e32 v7, 1.0, v7
	v_rcp_f32_e32 v7, v7
	s_nop 0
	v_mul_f32_e32 v2, v7, v2
	v_mul_f32_e32 v2, v6, v2
	v_lshlrev_b32_e32 v6, 16, v3
	v_mul_f32_e32 v7, 0xbfb8aa3b, v6
	v_exp_f32_e32 v7, v7
	v_and_b32_e32 v3, 0xffff0000, v3
	v_cvt_pk_bf16_f32 v2, v5, v2
	v_mul_f32_e32 v5, v120, v4
	v_add_f32_e32 v7, 1.0, v7
	v_rcp_f32_e32 v7, v7
	s_nop 0
	v_mul_f32_e32 v6, v7, v6
	v_mul_f32_e32 v7, 0xbfb8aa3b, v3
	v_exp_f32_e32 v7, v7
	v_mul_f32_e32 v5, v5, v6
	v_mul_f32_e32 v6, v121, v4
	v_add_f32_e32 v7, 1.0, v7
	v_rcp_f32_e32 v7, v7
	s_nop 0
	v_mul_f32_e32 v3, v7, v3
	v_mul_f32_e32 v3, v6, v3
	v_cvt_pk_bf16_f32 v3, v5, v3
	global_store_dwordx2 v[0:1], v[2:3], off offset:32
	global_load_dwordx2 v[2:3], v[0:1], off offset:64
	v_mul_f32_e32 v5, v114, v4
	s_waitcnt vmcnt(0)
	v_lshlrev_b32_e32 v6, 16, v2
	v_mul_f32_e32 v7, 0xbfb8aa3b, v6
	v_exp_f32_e32 v7, v7
	v_and_b32_e32 v2, 0xffff0000, v2
	v_add_f32_e32 v7, 1.0, v7
	v_rcp_f32_e32 v7, v7
	s_nop 0
	v_mul_f32_e32 v6, v7, v6
	v_mul_f32_e32 v7, 0xbfb8aa3b, v2
	v_exp_f32_e32 v7, v7
	v_mul_f32_e32 v5, v5, v6
	v_mul_f32_e32 v6, v115, v4
	v_add_f32_e32 v7, 1.0, v7
	v_rcp_f32_e32 v7, v7
	s_nop 0
	v_mul_f32_e32 v2, v7, v2
	v_mul_f32_e32 v2, v6, v2
	v_lshlrev_b32_e32 v6, 16, v3
	v_mul_f32_e32 v7, 0xbfb8aa3b, v6
	v_exp_f32_e32 v7, v7
	v_and_b32_e32 v3, 0xffff0000, v3
	v_cvt_pk_bf16_f32 v2, v5, v2
	v_mul_f32_e32 v5, v116, v4
	v_add_f32_e32 v7, 1.0, v7
	v_rcp_f32_e32 v7, v7
	s_nop 0
	v_mul_f32_e32 v6, v7, v6
	v_mul_f32_e32 v7, 0xbfb8aa3b, v3
	v_exp_f32_e32 v7, v7
	v_mul_f32_e32 v5, v5, v6
	v_mul_f32_e32 v6, v117, v4
	v_add_f32_e32 v7, 1.0, v7
	v_rcp_f32_e32 v7, v7
	s_nop 0
	v_mul_f32_e32 v3, v7, v3
	v_mul_f32_e32 v3, v6, v3
	v_cvt_pk_bf16_f32 v3, v5, v3
	global_store_dwordx2 v[0:1], v[2:3], off offset:64
	global_load_dwordx2 v[2:3], v[0:1], off offset:96
	v_mul_f32_e32 v5, v110, v4
	s_waitcnt vmcnt(0)
	v_lshlrev_b32_e32 v6, 16, v2
	v_mul_f32_e32 v7, 0xbfb8aa3b, v6
	v_exp_f32_e32 v7, v7
	v_and_b32_e32 v2, 0xffff0000, v2
	v_add_f32_e32 v7, 1.0, v7
	v_rcp_f32_e32 v7, v7
	s_nop 0
	v_mul_f32_e32 v6, v7, v6
	v_mul_f32_e32 v7, 0xbfb8aa3b, v2
	v_exp_f32_e32 v7, v7
	v_mul_f32_e32 v5, v5, v6
	v_mul_f32_e32 v6, v111, v4
	v_add_f32_e32 v7, 1.0, v7
	v_rcp_f32_e32 v7, v7
	s_nop 0
	v_mul_f32_e32 v2, v7, v2
	v_mul_f32_e32 v2, v6, v2
	v_lshlrev_b32_e32 v6, 16, v3
	v_mul_f32_e32 v7, 0xbfb8aa3b, v6
	v_exp_f32_e32 v7, v7
	v_cvt_pk_bf16_f32 v2, v5, v2
	v_mul_f32_e32 v5, v112, v4
	v_and_b32_e32 v3, 0xffff0000, v3
	v_add_f32_e32 v7, 1.0, v7
	v_rcp_f32_e32 v7, v7
	v_mul_f32_e32 v4, v113, v4
	v_mul_f32_e32 v6, v7, v6
	v_mul_f32_e32 v5, v5, v6
	v_mul_f32_e32 v6, 0xbfb8aa3b, v3
	v_exp_f32_e32 v6, v6
	s_nop 0
	v_add_f32_e32 v6, 1.0, v6
	v_rcp_f32_e32 v6, v6
	s_nop 0
	v_mul_f32_e32 v3, v6, v3
	v_mul_f32_e32 v3, v4, v3
	v_cvt_pk_bf16_f32 v3, v5, v3
	global_store_dwordx2 v[0:1], v[2:3], off offset:96
	s_cbranch_execz .LBB0_501
	v_mov_b32_e32 v198, 0x7f800000
	v_mov_b32_e32 v199, 0x7fc00000
	s_branch .LBB0_572
